# flag barrier also at the remaining half-block barrier sites of the mix phase (conv items, prep part 1 transposes, attention item boundaries), on top of the previous version
# speedup vs baseline: 1.0032x; 1.0008x over previous
; DI int my_tid() { int t = threadIdx.x & 255; asm volatile("" : "+v"(t)); return t; }
; DI int half_id() { return __builtin_amdgcn_readfirstlane((int)(threadIdx.x >> 8)); }
; DI void hsync() { hsync_impl(false); }
; DI void hsync_impl(const bool INIT) {
;     ...
;   asm volatile("s_waitcnt vmcnt(0) lgkmcnt(0)" ::: "memory");
;   if ((threadIdx.x & 63) == 0) {
;     const int h2 = 2 * half_id();
;     const unsigned gen = __hip_atomic_load(&hb[h2 + 1], __ATOMIC_RELAXED, __HIP_MEMORY_SCOPE_WORKGROUP);
;     const unsigned old = __hip_atomic_fetch_add(&hb[h2], 1u, __ATOMIC_RELAXED, __HIP_MEMORY_SCOPE_WORKGROUP);
;     if (old == 3u) {
;       __hip_atomic_store(&hb[h2], 0u, __ATOMIC_RELAXED, __HIP_MEMORY_SCOPE_WORKGROUP);
;       asm volatile("s_waitcnt vmcnt(0) lgkmcnt(0)" ::: "memory");
;       __hip_atomic_fetch_add(&hb[h2 + 1], 1u, __ATOMIC_RELAXED, __HIP_MEMORY_SCOPE_WORKGROUP);
;     } else {
;       while (__hip_atomic_load(&hb[h2 + 1], __ATOMIC_RELAXED, __HIP_MEMORY_SCOPE_WORKGROUP) == gen) __builtin_amdgcn_s_sleep(1);
;     }
;   }
;   asm volatile("s_waitcnt vmcnt(0) lgkmcnt(0)" ::: "memory");
; }
; template <bool MAPPED>
; DI void transpose_tile(const float* __restrict__ W, int K, int N, u16* __restrict__ Wt, int kt, int nt, char* smem) {
;   float* s = (float*)smem;
;   const int tid = my_tid();
;   hsync();
; #pragma unroll 4
;   for (int i = 0; i < 16; ++i) {
;     int idx = tid + 256 * i;
;     int kk = idx >> 6, pp = idx & 63;
;     int pcol = nt * 64 + pp;
;     int oc = MAPPED ? inproj_colmap(pcol) : pcol;
;     float v = 0.f;
;     if (oc >= 0) v = W[(size_t)(kt * 64 + kk) * N + oc];
.Lp1a_361:
	s_andn2_b64 vcc, exec, s[12:13]
	s_cbranch_vccnz .Lp1a_384
	v_mov_b32_e32 v0, v210
	s_waitcnt vmcnt(0) lgkmcnt(0)
	v_add_u32_e32 v251, 1, v251
	ds_write_b32 v249, v251
.Lfhs_17:
	ds_read_b128 v[244:247], v250
	s_waitcnt lgkmcnt(0)
	v_min3_u32 v248, v244, v245, v246
	v_min_u32_e32 v248, v248, v247
	v_cmp_ge_u32_e32 vcc, v248, v251
	s_cbranch_vccz .Lfhs_17
	s_lshl_b32 s2, s20, 1
	s_and_b32 s2, s2, 0x1fc0
	s_add_i32 s12, s2, 0xffffec00
	s_lshl_b32 s2, s20, 6
	v_and_b32_e32 v11, 63, v0
	s_and_b32 s2, s2, 0x7c0
	s_waitcnt vmcnt(0) lgkmcnt(0)
	v_or_b32_e32 v1, s2, v11
	v_lshlrev_b32_e32 v48, 2, v1
	v_add_u32_e32 v2, 0x200, v0
	v_add_u32_e32 v4, 0x400, v0
	v_add_u32_e32 v6, 0x600, v0
	s_mov_b32 s13, 1
	v_lshl_add_u64 v[8:9], s[74:75], 0, v[48:49]
	v_lshl_add_u32 v10, v11, 2, s33
	s_mov_b32 s14, s12
	v_mov_b32_e32 v1, v0
	v_mov_b32_e32 v3, v2
	v_mov_b32_e32 v5, v4
	v_mov_b32_e32 v7, v6
	s_mov_b32 s15, 0
	s_mov_b32 s16, 16

; DI int half_id() { return __builtin_amdgcn_readfirstlane((int)(threadIdx.x >> 8)); }
; DI void hsync_impl(const bool INIT) {
;     ...
;   asm volatile("s_waitcnt vmcnt(0) lgkmcnt(0)" ::: "memory");
;   if ((threadIdx.x & 63) == 0) {
;     const int h2 = 2 * half_id();
;     const unsigned gen = __hip_atomic_load(&hb[h2 + 1], __ATOMIC_RELAXED, __HIP_MEMORY_SCOPE_WORKGROUP);
;     const unsigned old = __hip_atomic_fetch_add(&hb[h2], 1u, __ATOMIC_RELAXED, __HIP_MEMORY_SCOPE_WORKGROUP);
;     if (old == 3u) {
;       __hip_atomic_store(&hb[h2], 0u, __ATOMIC_RELAXED, __HIP_MEMORY_SCOPE_WORKGROUP);
;       asm volatile("s_waitcnt vmcnt(0) lgkmcnt(0)" ::: "memory");
;       __hip_atomic_fetch_add(&hb[h2 + 1], 1u, __ATOMIC_RELAXED, __HIP_MEMORY_SCOPE_WORKGROUP);
;     } else {
;       while (__hip_atomic_load(&hb[h2 + 1], __ATOMIC_RELAXED, __HIP_MEMORY_SCOPE_WORKGROUP) == gen) __builtin_amdgcn_s_sleep(1);
;     }
;   }
;   asm volatile("s_waitcnt vmcnt(0) lgkmcnt(0)" ::: "memory");
; }
; template <bool MAPPED>
; DI void transpose_tile(const float* __restrict__ W, int K, int N, u16* __restrict__ Wt, int kt, int nt, char* smem) {
;     ...
; #pragma unroll 4
;   for (int i = 0; i < 16; ++i) {
;     int idx = tid + 256 * i;
;     int kk = idx >> 6, pp = idx & 63;
;     int pcol = nt * 64 + pp;
;     int oc = MAPPED ? inproj_colmap(pcol) : pcol;
;     float v = 0.f;
;     if (oc >= 0) v = W[(size_t)(kt * 64 + kk) * N + oc];
.Lfhs_16:
	ds_read_b128 v[244:247], v250
	s_waitcnt lgkmcnt(0)
	v_min3_u32 v248, v244, v245, v246
	v_min_u32_e32 v248, v248, v247
	v_cmp_ge_u32_e32 vcc, v248, v251
	s_cbranch_vccz .Lfhs_16
	s_lshl_b32 s2, s20, 2
	s_and_b32 s2, s2, 0x3fc0
	s_add_i32 s12, s2, 0xffffdc00
	s_lshl_b32 s2, s20, 6
	v_and_b32_e32 v11, 63, v0
	s_and_b32 s2, s2, 0x3c0
	s_waitcnt vmcnt(0) lgkmcnt(0)
	v_or_b32_e32 v1, s2, v11
	v_readlane_b32 s36, v253, 16
	v_lshlrev_b32_e32 v48, 2, v1
	v_readlane_b32 s50, v253, 30
	v_readlane_b32 s51, v253, 31
	v_add_u32_e32 v2, 0x200, v0
	v_add_u32_e32 v4, 0x400, v0
	v_add_u32_e32 v6, 0x600, v0
	v_lshl_add_u64 v[8:9], s[50:51], 0, v[48:49]
	v_lshl_add_u32 v10, v11, 2, s33
	s_mov_b32 s13, s12
	v_mov_b32_e32 v1, v0
	v_mov_b32_e32 v3, v2
	v_mov_b32_e32 v5, v4
	v_mov_b32_e32 v7, v6
	s_mov_b32 s14, 1
	s_mov_b32 s15, 0
	s_mov_b32 s16, 16
	v_readlane_b32 s37, v253, 17
	v_readlane_b32 s38, v253, 18
	v_readlane_b32 s39, v253, 19
	v_readlane_b32 s40, v253, 20
	v_readlane_b32 s41, v253, 21
	v_readlane_b32 s42, v253, 22
	v_readlane_b32 s43, v253, 23
	v_readlane_b32 s44, v253, 24
	v_readlane_b32 s45, v253, 25
	v_readlane_b32 s46, v253, 26
	v_readlane_b32 s47, v253, 27
	v_readlane_b32 s48, v253, 28
	v_readlane_b32 s49, v253, 29

; DI int half_id() { return __builtin_amdgcn_readfirstlane((int)(threadIdx.x >> 8)); }
; DI void hsync_impl(const bool INIT) {
;     ...
;   asm volatile("s_waitcnt vmcnt(0) lgkmcnt(0)" ::: "memory");
;   if ((threadIdx.x & 63) == 0) {
;     const int h2 = 2 * half_id();
;     const unsigned gen = __hip_atomic_load(&hb[h2 + 1], __ATOMIC_RELAXED, __HIP_MEMORY_SCOPE_WORKGROUP);
;     const unsigned old = __hip_atomic_fetch_add(&hb[h2], 1u, __ATOMIC_RELAXED, __HIP_MEMORY_SCOPE_WORKGROUP);
;     if (old == 3u) {
;       __hip_atomic_store(&hb[h2], 0u, __ATOMIC_RELAXED, __HIP_MEMORY_SCOPE_WORKGROUP);
;       asm volatile("s_waitcnt vmcnt(0) lgkmcnt(0)" ::: "memory");
;       __hip_atomic_fetch_add(&hb[h2 + 1], 1u, __ATOMIC_RELAXED, __HIP_MEMORY_SCOPE_WORKGROUP);
;     } else {
;       while (__hip_atomic_load(&hb[h2 + 1], __ATOMIC_RELAXED, __HIP_MEMORY_SCOPE_WORKGROUP) == gen) __builtin_amdgcn_s_sleep(1);
;     }
;   }
;   asm volatile("s_waitcnt vmcnt(0) lgkmcnt(0)" ::: "memory");
; }
; template <bool MAPPED>
; DI void transpose_tile(const float* __restrict__ W, int K, int N, u16* __restrict__ Wt, int kt, int nt, char* smem) {
;     ...
; #pragma unroll 4
;   for (int i = 0; i < 16; ++i) {
;     int idx = tid + 256 * i;
;     int kk = idx >> 6, pp = idx & 63;
;     int pcol = nt * 64 + pp;
;     int oc = MAPPED ? inproj_colmap(pcol) : pcol;
;     float v = 0.f;
;     if (oc >= 0) v = W[(size_t)(kt * 64 + kk) * N + oc];
.Lfhs_15:
	ds_read_b128 v[244:247], v250
	s_waitcnt lgkmcnt(0)
	v_min3_u32 v248, v244, v245, v246
	v_min_u32_e32 v248, v248, v247
	v_cmp_ge_u32_e32 vcc, v248, v251
	s_cbranch_vccz .Lfhs_15
	s_lshl_b32 s2, s20, 2
	s_and_b32 s2, s2, 0x3fc0
	s_add_i32 s12, s2, 0xffffde00
	s_lshl_b32 s2, s20, 6
	v_and_b32_e32 v11, 63, v0
	s_and_b32 s2, s2, 0x3c0
	s_waitcnt vmcnt(0) lgkmcnt(0)
	v_or_b32_e32 v1, s2, v11
	v_readlane_b32 s36, v253, 16
	v_lshlrev_b32_e32 v48, 2, v1
	v_readlane_b32 s48, v253, 28
	v_readlane_b32 s49, v253, 29
	v_add_u32_e32 v2, 0x200, v0
	v_add_u32_e32 v4, 0x400, v0
	v_add_u32_e32 v6, 0x600, v0
	v_lshl_add_u64 v[8:9], s[48:49], 0, v[48:49]
	v_lshl_add_u32 v10, v11, 2, s33
	s_mov_b32 s13, s12
	v_mov_b32_e32 v1, v0
	v_mov_b32_e32 v3, v2
	v_mov_b32_e32 v5, v4
	v_mov_b32_e32 v7, v6
	s_mov_b32 s14, 1
	s_mov_b32 s15, 0
	s_mov_b32 s16, 16
	v_readlane_b32 s37, v253, 17
	v_readlane_b32 s38, v253, 18
	v_readlane_b32 s39, v253, 19
	v_readlane_b32 s40, v253, 20
	v_readlane_b32 s41, v253, 21
	v_readlane_b32 s42, v253, 22
	v_readlane_b32 s43, v253, 23
	v_readlane_b32 s44, v253, 24
	v_readlane_b32 s45, v253, 25
	v_readlane_b32 s46, v253, 26
	v_readlane_b32 s47, v253, 27
	v_readlane_b32 s50, v253, 30
	v_readlane_b32 s51, v253, 31

; DI int half_id() { return __builtin_amdgcn_readfirstlane((int)(threadIdx.x >> 8)); }
; DI void hsync() { hsync_impl(false); }
; DI void hsync_impl(const bool INIT) {
;     ...
;   asm volatile("s_waitcnt vmcnt(0) lgkmcnt(0)" ::: "memory");
;   if ((threadIdx.x & 63) == 0) {
;     const int h2 = 2 * half_id();
;     const unsigned gen = __hip_atomic_load(&hb[h2 + 1], __ATOMIC_RELAXED, __HIP_MEMORY_SCOPE_WORKGROUP);
;     const unsigned old = __hip_atomic_fetch_add(&hb[h2], 1u, __ATOMIC_RELAXED, __HIP_MEMORY_SCOPE_WORKGROUP);
;     if (old == 3u) {
;       __hip_atomic_store(&hb[h2], 0u, __ATOMIC_RELAXED, __HIP_MEMORY_SCOPE_WORKGROUP);
;       asm volatile("s_waitcnt vmcnt(0) lgkmcnt(0)" ::: "memory");
;       __hip_atomic_fetch_add(&hb[h2 + 1], 1u, __ATOMIC_RELAXED, __HIP_MEMORY_SCOPE_WORKGROUP);
;     } else {
;       while (__hip_atomic_load(&hb[h2 + 1], __ATOMIC_RELAXED, __HIP_MEMORY_SCOPE_WORKGROUP) == gen) __builtin_amdgcn_s_sleep(1);
;     }
;   }
;   asm volatile("s_waitcnt vmcnt(0) lgkmcnt(0)" ::: "memory");
; }
; template <bool MAPPED>
; DI void transpose_tile(const float* __restrict__ W, int K, int N, u16* __restrict__ Wt, int kt, int nt, char* smem) {
;     ...
;   for (int i = 0; i < 16; ++i) {
;     int idx = tid + 256 * i;
;     int kk = idx >> 6, pp = idx & 63;
;     int pcol = nt * 64 + pp;
;     int oc = MAPPED ? inproj_colmap(pcol) : pcol;
;     float v = 0.f;
;     if (oc >= 0) v = W[(size_t)(kt * 64 + kk) * N + oc];
;     s[kk * 65 + pp] = v;
;   }
;   hsync();
; #pragma unroll 4
;   for (int i = 0; i < 16; ++i) {
;     int idx = tid + 256 * i;
;     int pp = idx >> 6, kk = idx & 63;
;     Wt[(size_t)(nt * 64 + pp) * K + kt * 64 + kk] = f2bf(s[kk * 65 + pp]);
.Lfhs_14:
	ds_read_b128 v[244:247], v250
	s_waitcnt lgkmcnt(0)
	v_min3_u32 v248, v244, v245, v246
	v_min_u32_e32 v248, v248, v247
	v_cmp_ge_u32_e32 vcc, v248, v251
	s_cbranch_vccz .Lfhs_14
	s_lshl_b32 s2, s20, 2
	s_and_b32 s2, s2, 0x3fc0
	s_add_i32 s12, s2, 0xffffe000
	s_lshl_b32 s2, s20, 6
	v_and_b32_e32 v11, 63, v0
	s_and_b32 s2, s2, 0x3c0
	s_waitcnt vmcnt(0) lgkmcnt(0)
	v_or_b32_e32 v1, s2, v11
	v_readlane_b32 s36, v253, 16
	v_lshlrev_b32_e32 v48, 2, v1
	v_readlane_b32 s38, v253, 18
	v_readlane_b32 s39, v253, 19
	v_add_u32_e32 v2, 0x200, v0
	v_add_u32_e32 v4, 0x400, v0
	v_add_u32_e32 v6, 0x600, v0
	v_lshl_add_u64 v[8:9], s[38:39], 0, v[48:49]
	v_lshl_add_u32 v10, v11, 2, s33
	s_mov_b32 s13, s12
	v_mov_b32_e32 v1, v0
	v_mov_b32_e32 v3, v2
	v_mov_b32_e32 v5, v4
	v_mov_b32_e32 v7, v6
	s_mov_b32 s14, 1
	s_mov_b32 s15, 0
	s_mov_b32 s16, 16
	v_readlane_b32 s37, v253, 17
	v_readlane_b32 s40, v253, 20
	v_readlane_b32 s41, v253, 21
	v_readlane_b32 s42, v253, 22
	v_readlane_b32 s43, v253, 23
	v_readlane_b32 s44, v253, 24
	v_readlane_b32 s45, v253, 25
	v_readlane_b32 s46, v253, 26
	v_readlane_b32 s47, v253, 27
	v_readlane_b32 s48, v253, 28
	v_readlane_b32 s49, v253, 29
	v_readlane_b32 s50, v253, 30
	v_readlane_b32 s51, v253, 31
.Lp1a_444:
	s_lshl_b32 s17, s15, 8
	s_lshl_b32 s18, s14, 8
	v_add_u32_e32 v13, s17, v0
	v_add_u32_e32 v12, s18, v1
	v_add_u32_e32 v14, s18, v3
	v_add_u32_e32 v15, s17, v2
	v_add_u32_e32 v16, s18, v5
	v_add_u32_e32 v17, s17, v4
	v_add_u32_e32 v18, s18, v7
	v_add_u32_e32 v19, s17, v6
	v_ashrrev_i32_e32 v28, 6, v13
	v_ashrrev_i32_e32 v29, 6, v12
	v_ashrrev_i32_e32 v30, 6, v15
	v_ashrrev_i32_e32 v31, 6, v14
	v_ashrrev_i32_e32 v32, 6, v17
	v_ashrrev_i32_e32 v33, 6, v16
	v_ashrrev_i32_e32 v34, 6, v19
	v_ashrrev_i32_e32 v35, 6, v18
	v_add_u32_e32 v14, s12, v28
	v_add_u32_e32 v12, s13, v29
	v_add_u32_e32 v16, s13, v31
	v_add_u32_e32 v18, s12, v30
	v_add_u32_e32 v20, s13, v33
	v_add_u32_e32 v22, s12, v32
	v_add_u32_e32 v24, s13, v35
	v_add_u32_e32 v26, s12, v34
	v_ashrrev_i32_e32 v15, 31, v14
	v_ashrrev_i32_e32 v13, 31, v12
	v_ashrrev_i32_e32 v19, 31, v18
	v_ashrrev_i32_e32 v17, 31, v16
	v_ashrrev_i32_e32 v23, 31, v22
	v_ashrrev_i32_e32 v21, 31, v20
	v_ashrrev_i32_e32 v27, 31, v26
	v_ashrrev_i32_e32 v25, 31, v24
	v_lshlrev_b64 v[14:15], 12, v[14:15]
	v_lshlrev_b64 v[12:13], 12, v[12:13]
	v_lshlrev_b64 v[16:17], 12, v[16:17]
	v_lshlrev_b64 v[18:19], 12, v[18:19]
	v_lshlrev_b64 v[20:21], 12, v[20:21]
	v_lshlrev_b64 v[22:23], 12, v[22:23]
	v_lshlrev_b64 v[24:25], 12, v[24:25]
	v_lshlrev_b64 v[26:27], 12, v[26:27]
	v_lshl_add_u64 v[14:15], v[8:9], 0, v[14:15]
	v_lshl_add_u64 v[12:13], v[8:9], 0, v[12:13]
	v_lshl_add_u64 v[18:19], v[8:9], 0, v[18:19]
	v_lshl_add_u64 v[16:17], v[8:9], 0, v[16:17]
	v_lshl_add_u64 v[22:23], v[8:9], 0, v[22:23]
	v_lshl_add_u64 v[20:21], v[8:9], 0, v[20:21]
	v_lshl_add_u64 v[26:27], v[8:9], 0, v[26:27]
	v_lshl_add_u64 v[24:25], v[8:9], 0, v[24:25]
	global_load_dword v36, v[14:15], off
	global_load_dword v37, v[12:13], off
	global_load_dword v38, v[18:19], off
	global_load_dword v39, v[16:17], off
	global_load_dword v40, v[22:23], off
	global_load_dword v41, v[20:21], off
	global_load_dword v42, v[26:27], off
	global_load_dword v43, v[24:25], off
	s_add_i32 s15, s15, 8
	s_add_i32 s14, s14, 8
	s_add_i32 s16, s16, -8
	s_cmp_lg_u32 s16, 0
	v_mad_u64_u32 v[12:13], s[18:19], v28, s29, v[10:11]
	v_mad_u64_u32 v[14:15], s[18:19], v29, s29, v[10:11]
	v_mad_u64_u32 v[16:17], s[18:19], v30, s29, v[10:11]
	v_mad_u64_u32 v[18:19], s[18:19], v31, s29, v[10:11]
	v_mad_u64_u32 v[20:21], s[18:19], v32, s29, v[10:11]
	v_mad_u64_u32 v[22:23], s[18:19], v33, s29, v[10:11]
	v_mad_u64_u32 v[24:25], s[18:19], v34, s29, v[10:11]
	v_mad_u64_u32 v[26:27], s[18:19], v35, s29, v[10:11]
	s_waitcnt vmcnt(7)
	ds_write_b32 v12, v36
	s_waitcnt vmcnt(6)
	ds_write_b32 v14, v37
	s_waitcnt vmcnt(5)
	ds_write_b32 v16, v38
	s_waitcnt vmcnt(4)
	ds_write_b32 v18, v39
	s_waitcnt vmcnt(3)
	ds_write_b32 v20, v40
	s_waitcnt vmcnt(2)
	ds_write_b32 v22, v41
	s_waitcnt vmcnt(1)
	ds_write_b32 v24, v42
	s_waitcnt vmcnt(0)
	ds_write_b32 v26, v43
	s_cbranch_scc1 .Lp1a_444
	s_waitcnt vmcnt(0) lgkmcnt(0)
	v_add_u32_e32 v251, 1, v251
	ds_write_b32 v249, v251
.Lfhs_13:
	ds_read_b128 v[244:247], v250
	s_waitcnt lgkmcnt(0)
	v_min3_u32 v248, v244, v245, v246
	v_min_u32_e32 v248, v248, v247
	v_cmp_ge_u32_e32 vcc, v248, v251
	s_cbranch_vccz .Lfhs_13
	s_mov_b32 s13, s3
	s_lshl_b64 s[12:13], s[12:13], 1
	s_waitcnt vmcnt(0) lgkmcnt(0)
	s_add_u32 s12, s27, s12
	s_addc_u32 s13, s28, s13
	v_lshlrev_b32_e32 v48, 1, v11
	v_mov_b32_e32 v10, s33
	s_mov_b32 s14, 1
	v_lshl_add_u64 v[8:9], s[12:13], 0, v[48:49]
	v_mad_u32_u24 v10, v11, s29, v10
	s_mov_b32 s12, s2
	s_mov_b32 s13, 0
	s_mov_b32 s15, 16

; DI void hsync() { hsync_impl(false); }
; DI float fexp2(float x) { return __builtin_amdgcn_exp2f(x); }
; DI void attn_item(const Params& p, int item, char* smem) {
;     ...
;   const int bg = item & 7, q32 = 127 - (item >> 3);
;   const int b = bg >> 1, g = bg & 1;
;   const int t0 = q32 * 32;
;   const int head = g * 4 + wave;
;   const int t = t0 + lr;
;   const size_t row = (size_t)b * 4096 + t;
;   const int qb = t0 >> 6;
;   bf16x8 qf[4];
; #pragma unroll
;   for (int ks = 0; ks < 4; ++ks) qf[ks] = *(const bf16x8*)(Q + row * 512 + head * 64 + ks * 16 + hh * 8);
;   float* ot_s = (float*)(sel8 + 256) + wave * 32 * 64 + lane;
;   const float slope2 = fexp2(-(float)(head + 1)) * LOG2E;
;   const float gc = NG[row * 32 + head], gs = NG[row * 32 + 8 + head], gw = NG[row * 32 + 16 + head];
;   f32x16 O[2];
;   hsync();
;   for (int i = tid; i < 32 * 65; i += 256) imp_s[i] = 0u;
.LBB0_533:
	s_and_b32 s0, s78, 1
	s_sub_i32 s1, s56, s94
	s_cmp_eq_u32 s0, 0
	s_cselect_b32 s79, s94, s1
	s_cmpk_gt_u32 s79, 0x3ff
	s_cbranch_scc1 .LBB0_532
	s_not_b32 s0, s79
	v_mov_b32_e32 v130, v210
	s_lshl_b32 s0, s0, 2
	s_and_b32 s57, s0, 0xfe0
	v_and_b32_e32 v129, 31, v130
	s_lshl_b32 s0, s79, 11
	v_ashrrev_i32_e32 v133, 6, v130
	s_and_b32 s90, s79, 1
	s_waitcnt vmcnt(0)
	v_or_b32_e32 v157, s57, v129
	s_and_b32 s38, s0, 0x3000
	v_lshl_add_u32 v0, s90, 2, v133
	v_or_b32_e32 v6, s38, v157
	v_readlane_b32 s0, v253, 57
	v_lshlrev_b32_e32 v96, 10, v6
	v_readlane_b32 s1, v253, 58
	v_lshlrev_b32_e32 v98, 6, v0
	v_bfe_u32 v128, v130, 5, 1
	v_lshl_add_u64 v[2:3], s[0:1], 0, v[96:97]
	v_ashrrev_i32_e32 v99, 31, v98
	v_lshl_add_u64 v[2:3], v[98:99], 1, v[2:3]
	v_lshlrev_b32_e32 v4, 4, v128
	v_mov_b32_e32 v5, v97
	v_lshl_add_u64 v[2:3], v[2:3], 0, v[4:5]
	v_readlane_b32 s0, v252, 5
	global_load_dwordx4 v[64:67], v[2:3], off
	global_load_dwordx4 v[68:71], v[2:3], off offset:32
	global_load_dwordx4 v[72:75], v[2:3], off offset:64
	global_load_dwordx4 v[76:79], v[2:3], off offset:96
	v_lshlrev_b32_e32 v2, 7, v6
	v_mov_b32_e32 v3, v97
	v_readlane_b32 s1, v252, 6
	v_ashrrev_i32_e32 v1, 31, v0
	s_nop 0
	v_lshl_add_u64 v[2:3], s[0:1], 0, v[2:3]
	v_lshl_add_u64 v[2:3], v[0:1], 2, v[2:3]
	global_load_dword v132, v[2:3], off
	global_load_dword v164, v[2:3], off offset:32
	global_load_dword v156, v[2:3], off offset:64
	s_waitcnt vmcnt(0) lgkmcnt(0)
	v_add_u32_e32 v251, 1, v251
	ds_write_b32 v249, v251
.Lfhs_12:
	ds_read_b128 v[244:247], v250
	s_waitcnt lgkmcnt(0)
	v_min3_u32 v248, v244, v245, v246
	v_min_u32_e32 v248, v248, v247
	v_cmp_ge_u32_e32 vcc, v248, v251
	s_cbranch_vccz .Lfhs_12
	s_waitcnt vmcnt(0) lgkmcnt(0)
	s_movk_i32 s0, 0x820
	v_and_b32_e32 v134, 63, v130
	v_lshlrev_b32_e32 v1, 3, v128
	v_cmp_gt_i32_e32 vcc, s0, v130
	s_and_saveexec_b64 s[0:1], vcc
	s_cbranch_execz .LBB0_546
	v_readlane_b32 s8, v252, 7
	v_add_u32_e32 v3, 0xffffff00, v130
	s_nop 0
	v_lshl_add_u32 v2, v130, 2, s8
	s_mov_b64 s[8:9], 0

; DI void hsync() { hsync_impl(false); }
; DI void attn_item(const Params& p, int item, char* smem) {
;     ...
; #pragma unroll
;     for (int e = 0; e < 16; ++e) { ot_s[e * 64] = O[0][e] * gc; ot_s[(16 + e) * 64] = O[1][e] * gc; }
;   }
;   hsync();
;   {
;     const int tl = tid >> 3, part = tid & 7;
;     unsigned bits = 0;
;     if (qb <= 15) {
; #pragma unroll
;       for (int jj = 0; jj < 8; ++jj) if (part * 8 + jj <= qb) bits |= 1u << jj;
;     } else {
;       unsigned mine[8];
;       int cnt[8];
; #pragma unroll
;       for (int jj = 0; jj < 8; ++jj) { mine[jj] = (imp_s[tl * 65 + part * 8 + jj] << 6) | (unsigned)(63 - (part * 8 + jj)); cnt[jj] = 0; }
;       for (int jp = 1; jp <= qb - 2; ++jp) {
;         const unsigned v = (imp_s[tl * 65 + jp] << 6) | (unsigned)(63 - jp);
.LBB0_574:
	v_lshlrev_b32_e32 v32, 13, v133
	v_lshlrev_b32_e32 v33, 2, v134
	v_add3_u32 v32, s33, v32, v33
	s_nop 4
	v_mul_f32_e32 v0, v132, v0
	v_mul_f32_e32 v1, v132, v1
	v_add_u32_e32 v117, 0x80, v32
	v_mul_f32_e32 v16, v132, v16
	ds_write2st64_b32 v117, v0, v1 offset0:177 offset1:178
	v_mul_f32_e32 v0, v132, v17
	ds_write2st64_b32 v117, v16, v0 offset0:193 offset1:194
	v_mul_f32_e32 v0, v132, v2
	v_mul_f32_e32 v2, v132, v3
	v_mul_f32_e32 v1, v132, v18
	ds_write2st64_b32 v117, v0, v2 offset0:179 offset1:180
	v_mul_f32_e32 v0, v132, v19
	ds_write2st64_b32 v117, v1, v0 offset0:195 offset1:196
	v_mul_f32_e32 v0, v132, v4
	v_mul_f32_e32 v2, v132, v5
	v_mul_f32_e32 v1, v132, v20
	ds_write2st64_b32 v117, v0, v2 offset0:181 offset1:182
	v_mul_f32_e32 v0, v132, v21
	ds_write2st64_b32 v117, v1, v0 offset0:197 offset1:198
	v_mul_f32_e32 v0, v132, v6
	v_mul_f32_e32 v2, v132, v7
	v_mul_f32_e32 v1, v132, v22
	ds_write2st64_b32 v117, v0, v2 offset0:183 offset1:184
	v_mul_f32_e32 v0, v132, v23
	ds_write2st64_b32 v117, v1, v0 offset0:199 offset1:200
	v_mul_f32_e32 v0, v132, v8
	v_mul_f32_e32 v2, v132, v9
	v_mul_f32_e32 v1, v132, v24
	ds_write2st64_b32 v117, v0, v2 offset0:185 offset1:186
	v_mul_f32_e32 v0, v132, v25
	ds_write2st64_b32 v117, v1, v0 offset0:201 offset1:202
	v_mul_f32_e32 v0, v132, v10
	v_mul_f32_e32 v2, v132, v11
	v_mul_f32_e32 v1, v132, v26
	ds_write2st64_b32 v117, v0, v2 offset0:187 offset1:188
	v_mul_f32_e32 v0, v132, v27
	ds_write2st64_b32 v117, v1, v0 offset0:203 offset1:204
	v_mul_f32_e32 v0, v132, v12
	v_mul_f32_e32 v2, v132, v13
	v_mul_f32_e32 v1, v132, v28
	ds_write2st64_b32 v117, v0, v2 offset0:189 offset1:190
	v_mul_f32_e32 v0, v132, v29
	ds_write2st64_b32 v117, v1, v0 offset0:205 offset1:206
	v_mul_f32_e32 v0, v132, v14
	v_mul_f32_e32 v2, v132, v15
	v_mul_f32_e32 v1, v132, v30
	ds_write2st64_b32 v117, v0, v2 offset0:191 offset1:192
	v_mul_f32_e32 v0, v132, v31
	ds_write2st64_b32 v117, v1, v0 offset0:207 offset1:208
	s_waitcnt vmcnt(0) lgkmcnt(0)
	v_add_u32_e32 v251, 1, v251
	ds_write_b32 v249, v251
.Lfhs_9:
	ds_read_b128 v[244:247], v250
	s_waitcnt lgkmcnt(0)
	v_min3_u32 v248, v244, v245, v246
	v_min_u32_e32 v248, v248, v247
	v_cmp_ge_u32_e32 vcc, v248, v251
	s_cbranch_vccz .Lfhs_9
	s_waitcnt vmcnt(0) lgkmcnt(0)
	s_lshr_b32 s86, s57, 6
	v_and_b32_e32 v17, 7, v130
	s_cmpk_gt_u32 s57, 0x3ff
	v_lshlrev_b32_e32 v16, 3, v17
	s_mov_b64 s[0:1], -1
	s_cbranch_scc0 .LBB0_593
	s_movk_i32 s0, 0x104
	v_mul_lo_u32 v23, v112, s0
	v_add_u32_e32 v27, s33, v23
	v_lshl_add_u32 v4, v16, 2, v27
	v_add_u32_e32 v0, 0x9000, v4
	ds_read2_b32 v[0:1], v0 offset1:7
	s_add_i32 s0, s86, -4
	s_mov_b32 s8, 2
	s_cmp_lt_u32 s0, 2
	s_waitcnt lgkmcnt(0)
	v_lshlrev_b32_e32 v0, 6, v0
	v_bitop3_b32 v18, v0, 63, v16 bitop3:0x36
	v_add_u32_e32 v0, 0x9004, v4
	ds_read2_b32 v[2:3], v0 offset1:1
	s_waitcnt lgkmcnt(0)
	v_lshlrev_b32_e32 v0, 6, v3
	v_lshlrev_b32_e32 v2, 6, v2
	v_sub_u32_e32 v0, v0, v16
	v_sub_u32_e32 v2, v2, v16
	v_add_u32_e32 v19, 61, v0
	v_add_u32_e32 v0, 0x900c, v4
	v_add_u32_e32 v20, 62, v2
	ds_read2_b32 v[2:3], v0 offset1:1
	s_waitcnt lgkmcnt(0)
	v_lshlrev_b32_e32 v0, 6, v3
	v_lshlrev_b32_e32 v2, 6, v2
	v_sub_u32_e32 v0, v0, v16
	v_sub_u32_e32 v2, v2, v16
	v_add_u32_e32 v21, 59, v0
	v_add_u32_e32 v0, 0x9014, v4
	v_add_u32_e32 v22, 60, v2
	ds_read2_b32 v[2:3], v0 offset1:1
	s_waitcnt lgkmcnt(0)
	v_lshlrev_b32_e32 v0, 6, v3
	v_sub_u32_e32 v0, v0, v16
	v_lshlrev_b32_e32 v2, 6, v2
	v_add_u32_e32 v24, 57, v0
	v_lshlrev_b32_e32 v0, 6, v1
	v_sub_u32_e32 v2, v2, v16
	v_sub_u32_e32 v0, v0, v16
	v_add_u32_e32 v25, 58, v2
	v_add_u32_e32 v26, 56, v0
	s_cbranch_scc1 .LBB0_657
	s_lshr_b32 s0, s0, 1
	s_add_i32 s0, s0, 1
	s_and_b32 s11, s0, -2
	v_readlane_b32 s0, v252, 8
	s_mov_b32 s9, 1
	s_mov_b32 s10, 0
	v_add_u32_e32 v28, s0, v23
	v_mov_b32_e32 v14, 0
	v_mov_b32_e32 v15, 0
	v_mov_b32_e32 v12, 0
	v_mov_b32_e32 v13, 0
	v_mov_b32_e32 v10, 0
	v_mov_b32_e32 v11, 0
	v_mov_b32_e32 v8, 0
	v_mov_b32_e32 v9, 0
	v_mov_b32_e32 v6, 0
	v_mov_b32_e32 v7, 0
	v_mov_b32_e32 v4, 0
	v_mov_b32_e32 v5, 0
	v_mov_b32_e32 v2, 0
	v_mov_b32_e32 v3, 0
	v_mov_b32_e32 v0, 0
	v_mov_b32_e32 v1, 0

; DI void hsync() { hsync_impl(false); }
; DI void attn_item(const Params& p, int item, char* smem) {
;     ...
;     sel8[tl * 8 + part] = (unsigned char)bits;
;   }
;   hsync();
;   {
;     const unsigned* sel32 = (const unsigned*)sel8;
;     const unsigned mylo = sel32[lr * 2], myhi = sel32[lr * 2 + 1];
;     unsigned alo = mylo, ahi = myhi;
; #pragma unroll
;     for (int o = 16; o > 0; o >>= 1) { alo |= __shfl_xor(alo, o); ahi |= __shfl_xor(ahi, o); }
;     alo = __builtin_amdgcn_readfirstlane(alo);
;     ahi = __builtin_amdgcn_readfirstlane(ahi);
;     m = -1e30f; l = 0.f;
; #pragma unroll
;     for (int e = 0; e < 16; ++e) { O[0][e] = 0.f; O[1][e] = 0.f; }
;     u64 am = ((u64)ahi << 32) | (u64)alo;
;     int j = -1;
;     if (am) { j = __builtin_ctzll(am); am &= am - 1; }
.LBB0_595:
	v_add_u32_e32 v1, s33, v130
	ds_write_b8 v1, v0 offset:45184
	s_waitcnt vmcnt(0) lgkmcnt(0)
	v_add_u32_e32 v251, 1, v251
	ds_write_b32 v249, v251
.Lfhs_8:
	ds_read_b128 v[244:247], v250
	s_waitcnt lgkmcnt(0)
	v_min3_u32 v248, v244, v245, v246
	v_min_u32_e32 v248, v248, v247
	v_cmp_ge_u32_e32 vcc, v248, v251
	s_cbranch_vccz .Lfhs_8
	s_waitcnt vmcnt(0) lgkmcnt(0)
	v_lshl_add_u32 v0, v129, 3, s33
	ds_read_b64 v[62:63], v0 offset:45184
	v_xor_b32_e32 v0, 16, v101
	v_cmp_lt_i32_e32 vcc, v0, v131
	v_xor_b32_e32 v2, 8, v101
	s_mov_b64 s[88:89], -1
	v_cndmask_b32_e32 v0, v101, v0, vcc
	v_lshlrev_b32_e32 v0, 2, v0
	s_waitcnt lgkmcnt(0)
	ds_bpermute_b32 v1, v0, v62
	ds_bpermute_b32 v0, v0, v63
	v_cmp_lt_i32_e32 vcc, v2, v131
	s_waitcnt lgkmcnt(1)
	v_or_b32_e32 v1, v1, v62
	v_cndmask_b32_e32 v2, v101, v2, vcc
	s_waitcnt lgkmcnt(0)
	v_or_b32_e32 v0, v0, v63
	v_lshlrev_b32_e32 v2, 2, v2
	ds_bpermute_b32 v3, v2, v1
	ds_bpermute_b32 v2, v2, v0
	s_waitcnt lgkmcnt(1)
	v_or_b32_e32 v1, v3, v1
	s_waitcnt lgkmcnt(0)
	v_or_b32_e32 v0, v2, v0
	v_xor_b32_e32 v2, 4, v101
	v_cmp_lt_i32_e32 vcc, v2, v131
	s_nop 1
	v_cndmask_b32_e32 v2, v101, v2, vcc
	v_lshlrev_b32_e32 v2, 2, v2
	ds_bpermute_b32 v3, v2, v1
	ds_bpermute_b32 v2, v2, v0
	s_waitcnt lgkmcnt(1)
	v_or_b32_e32 v1, v3, v1
	s_waitcnt lgkmcnt(0)
	v_or_b32_e32 v0, v2, v0
	v_xor_b32_e32 v2, 2, v101
	v_cmp_lt_i32_e32 vcc, v2, v131
	s_nop 1
	v_cndmask_b32_e32 v2, v101, v2, vcc
	v_lshlrev_b32_e32 v2, 2, v2
	ds_bpermute_b32 v3, v2, v1
	ds_bpermute_b32 v2, v2, v0
	s_waitcnt lgkmcnt(1)
	v_or_b32_e32 v1, v3, v1
	s_waitcnt lgkmcnt(0)
	v_or_b32_e32 v0, v2, v0
	v_xor_b32_e32 v2, 1, v101
	v_cmp_lt_i32_e32 vcc, v2, v131
	s_nop 1
	v_cndmask_b32_e32 v2, v101, v2, vcc
	v_lshlrev_b32_e32 v2, 2, v2
	ds_bpermute_b32 v3, v2, v1
	ds_bpermute_b32 v2, v2, v0
	s_waitcnt lgkmcnt(1)
	v_or_b32_e32 v1, v3, v1
	s_waitcnt lgkmcnt(0)
	v_or_b32_e32 v0, v2, v0
	v_readfirstlane_b32 s0, v1
	v_readfirstlane_b32 s1, v0
	s_ff1_i32_b64 s80, s[0:1]
	s_cmp_lg_u64 s[0:1], 0
	s_cselect_b32 s81, s80, -1
	s_cmp_lt_i32 s81, 0
	s_cselect_b64 s[10:11], -1, 0
	s_cmp_gt_i32 s81, -1
	s_cbranch_scc1 .LBB0_606
	s_lshl_b32 s8, s90, 6
	s_mov_b32 s9, s18
	s_mov_b64 s[88:89], 0

; DI void hsync() { hsync_impl(false); }
; DI void conv_item(const Params& p, int item, char* smem) {
;     ...
;   unsigned rowv[46];
; #pragma unroll
;   for (int r = 0; r < 46; ++r) {
;     int tt = t0 - 30 + r;
;     rowv[r] = 0u;
;     if (tt >= 0) rowv[r] = *(const unsigned*)(GLU + ((size_t)(b * 4096 + tt)) * 512 + c0);
;   }
;   hsync();
; #pragma unroll
;   for (int pass = 0; pass < 2; ++pass) {
;     float w[31];
; #pragma unroll
;     for (int k = 0; k < 31; ++k) w[k] = p.w_dw[k * 512 + c0 + pass];
.LBB0_723:
	s_ashr_i32 s13, s12, 31
	s_lshl_b64 s[0:1], s[12:13], 10
	v_lshl_add_u64 v[8:9], v[6:7], 0, s[0:1]
	s_or_b32 s0, s12, 1
	s_ashr_i32 s1, s0, 31
	s_lshl_b64 s[0:1], s[0:1], 10
	v_lshl_add_u64 v[10:11], v[6:7], 0, s[0:1]
	s_or_b32 s0, s12, 2
	s_ashr_i32 s1, s0, 31
	s_lshl_b64 s[0:1], s[0:1], 10
	v_lshl_add_u64 v[12:13], v[6:7], 0, s[0:1]
	s_or_b32 s0, s12, 3
	s_ashr_i32 s1, s0, 31
	s_lshl_b64 s[0:1], s[0:1], 10
	v_lshl_add_u64 v[14:15], v[6:7], 0, s[0:1]
	s_or_b32 s0, s12, 4
	s_ashr_i32 s1, s0, 31
	s_lshl_b64 s[0:1], s[0:1], 10
	v_lshl_add_u64 v[16:17], v[6:7], 0, s[0:1]
	s_or_b32 s0, s12, 5
	s_ashr_i32 s1, s0, 31
	s_lshl_b64 s[0:1], s[0:1], 10
	v_lshl_add_u64 v[18:19], v[6:7], 0, s[0:1]
	s_or_b32 s0, s12, 6
	s_ashr_i32 s1, s0, 31
	s_lshl_b64 s[0:1], s[0:1], 10
	v_lshl_add_u64 v[20:21], v[6:7], 0, s[0:1]
	s_or_b32 s0, s12, 7
	s_ashr_i32 s1, s0, 31
	s_lshl_b64 s[0:1], s[0:1], 10
	v_lshl_add_u64 v[22:23], v[6:7], 0, s[0:1]
	s_or_b32 s0, s12, 8
	s_ashr_i32 s1, s0, 31
	s_lshl_b64 s[0:1], s[0:1], 10
	global_load_dword v171, v[8:9], off
	global_load_dword v170, v[10:11], off
	global_load_dword v168, v[12:13], off
	global_load_dword v165, v[14:15], off
	global_load_dword v162, v[16:17], off
	global_load_dword v161, v[18:19], off
	global_load_dword v160, v[20:21], off
	global_load_dword v117, v[22:23], off
	v_lshl_add_u64 v[8:9], v[6:7], 0, s[0:1]
	s_or_b32 s0, s12, 9
	s_ashr_i32 s1, s0, 31
	s_lshl_b64 s[0:1], s[0:1], 10
	v_lshl_add_u64 v[10:11], v[6:7], 0, s[0:1]
	s_or_b32 s0, s12, 10
	s_ashr_i32 s1, s0, 31
	s_lshl_b64 s[0:1], s[0:1], 10
	v_lshl_add_u64 v[12:13], v[6:7], 0, s[0:1]
	s_or_b32 s0, s12, 11
	s_ashr_i32 s1, s0, 31
	s_lshl_b64 s[0:1], s[0:1], 10
	v_lshl_add_u64 v[14:15], v[6:7], 0, s[0:1]
	s_or_b32 s0, s12, 12
	s_ashr_i32 s1, s0, 31
	s_lshl_b64 s[0:1], s[0:1], 10
	v_lshl_add_u64 v[16:17], v[6:7], 0, s[0:1]
	s_or_b32 s0, s12, 13
	s_ashr_i32 s1, s0, 31
	s_lshl_b64 s[0:1], s[0:1], 10
	v_lshl_add_u64 v[18:19], v[6:7], 0, s[0:1]
	s_or_b32 s0, s12, 14
	s_ashr_i32 s1, s0, 31
	s_lshl_b64 s[0:1], s[0:1], 10
	v_lshl_add_u64 v[20:21], v[6:7], 0, s[0:1]
	s_or_b32 s0, s12, 15
	s_ashr_i32 s1, s0, 31
	s_lshl_b64 s[0:1], s[0:1], 10
	v_lshl_add_u64 v[6:7], v[6:7], 0, s[0:1]
	global_load_dword v159, v[8:9], off
	global_load_dword v158, v[10:11], off
	global_load_dword v111, v[12:13], off
	global_load_dword v109, v[14:15], off
	global_load_dword v107, v[16:17], off
	global_load_dword v105, v[18:19], off
	global_load_dword v103, v[20:21], off
	global_load_dword v157, v[6:7], off
	s_waitcnt vmcnt(0) lgkmcnt(0)
	v_add_u32_e32 v251, 1, v251
	ds_write_b32 v249, v251
.Lfhs_5:
	ds_read_b128 v[244:247], v250
	s_waitcnt lgkmcnt(0)
	v_min3_u32 v248, v244, v245, v246
	v_min_u32_e32 v248, v248, v247
	v_cmp_ge_u32_e32 vcc, v248, v251
	s_cbranch_vccz .Lfhs_5
	v_readlane_b32 s36, v253, 16
	v_add_u32_e32 v6, 0x400, v4
	v_readlane_b32 s40, v253, 20
	v_readlane_b32 s41, v253, 21
	v_ashrrev_i32_e32 v7, 31, v6
	s_waitcnt vmcnt(0) lgkmcnt(0)
	s_waitcnt vmcnt(16)
	v_lshlrev_b32_e32 v174, 16, v25
	v_lshl_add_u64 v[12:13], v[6:7], 2, s[40:41]
	v_add_u32_e32 v6, 0x600, v4
	v_ashrrev_i32_e32 v7, 31, v6
	v_lshl_add_u64 v[14:15], v[6:7], 2, s[40:41]
	v_add_u32_e32 v6, 0x800, v4
	v_ashrrev_i32_e32 v7, 31, v6
	v_lshl_add_u64 v[16:17], v[6:7], 2, s[40:41]
	v_add_u32_e32 v6, 0xa00, v4
	v_ashrrev_i32_e32 v7, 31, v6
	v_lshl_add_u64 v[18:19], v[6:7], 2, s[40:41]
	v_add_u32_e32 v6, 0xc00, v4
	v_ashrrev_i32_e32 v7, 31, v6
	v_lshl_add_u64 v[20:21], v[6:7], 2, s[40:41]
	v_add_u32_e32 v6, 0xe00, v4
	v_ashrrev_i32_e32 v7, 31, v6
	v_lshl_add_u64 v[22:23], v[6:7], 2, s[40:41]
	v_add_u32_e32 v6, 0x1000, v4
	v_ashrrev_i32_e32 v7, 31, v6
	v_lshl_add_u64 v[30:31], v[6:7], 2, s[40:41]
	v_add_u32_e32 v6, 0x1200, v4
	v_ashrrev_i32_e32 v7, 31, v6
	v_lshl_add_u64 v[32:33], v[6:7], 2, s[40:41]
	v_add_u32_e32 v6, 0x1400, v4
	v_ashrrev_i32_e32 v7, 31, v6
	v_lshl_add_u64 v[34:35], v[6:7], 2, s[40:41]
	v_add_u32_e32 v6, 0x1600, v4
	v_ashrrev_i32_e32 v7, 31, v6
	v_lshl_add_u64 v[36:37], v[6:7], 2, s[40:41]
	v_add_u32_e32 v6, 0x1800, v4
	v_ashrrev_i32_e32 v7, 31, v6
	v_lshl_add_u64 v[38:39], v[6:7], 2, s[40:41]
	v_add_u32_e32 v6, 0x1a00, v4
	v_ashrrev_i32_e32 v7, 31, v6
	v_lshl_add_u64 v[40:41], v[6:7], 2, s[40:41]
	v_add_u32_e32 v6, 0x1c00, v4
	v_ashrrev_i32_e32 v7, 31, v6
	v_lshl_add_u64 v[42:43], v[6:7], 2, s[40:41]
	v_add_u32_e32 v6, 0x1e00, v4
	v_ashrrev_i32_e32 v7, 31, v6
	v_lshl_add_u64 v[44:45], v[6:7], 2, s[40:41]
	v_add_u32_e32 v6, 0x2000, v4
	v_ashrrev_i32_e32 v7, 31, v6
	v_lshl_add_u64 v[46:47], v[6:7], 2, s[40:41]
	v_add_u32_e32 v6, 0x2200, v4
	v_ashrrev_i32_e32 v7, 31, v6
	v_lshl_add_u64 v[50:51], v[6:7], 2, s[40:41]
	v_add_u32_e32 v6, 0x2400, v4
	v_ashrrev_i32_e32 v7, 31, v6
	v_lshl_add_u64 v[52:53], v[6:7], 2, s[40:41]
	v_add_u32_e32 v6, 0x2600, v4
	v_ashrrev_i32_e32 v7, 31, v6
	v_lshl_add_u64 v[76:77], v[6:7], 2, s[40:41]
	v_add_u32_e32 v6, 0x2800, v4
	v_ashrrev_i32_e32 v7, 31, v6
	v_lshl_add_u64 v[80:81], v[6:7], 2, s[40:41]
	v_add_u32_e32 v6, 0x2a00, v4
	v_ashrrev_i32_e32 v7, 31, v6
	v_lshl_add_u64 v[82:83], v[6:7], 2, s[40:41]
	v_add_u32_e32 v6, 0x2c00, v4
	v_ashrrev_i32_e32 v7, 31, v6
	v_lshl_add_u64 v[84:85], v[6:7], 2, s[40:41]
	v_add_u32_e32 v6, 0x2e00, v4
	v_ashrrev_i32_e32 v7, 31, v6
	v_lshl_add_u64 v[86:87], v[6:7], 2, s[40:41]
	v_add_u32_e32 v6, 0x3000, v4
	v_ashrrev_i32_e32 v7, 31, v6
	v_lshl_add_u64 v[88:89], v[6:7], 2, s[40:41]
	v_add_u32_e32 v6, 0x3200, v4
	v_ashrrev_i32_e32 v7, 31, v6
	v_lshl_add_u64 v[90:91], v[6:7], 2, s[40:41]
	v_add_u32_e32 v6, 0x3400, v4
	v_ashrrev_i32_e32 v7, 31, v6
	v_lshl_add_u64 v[92:93], v[6:7], 2, s[40:41]
	v_add_u32_e32 v6, 0x3600, v4
; DI float bflo(unsigned u) { return __uint_as_float(u << 16); }
; DI float bfhi(unsigned u) { return __uint_as_float(u & 0xffff0000u); }
; DI void conv_item(const Params& p, int item, char* smem) {
;     ...
;   for (int pass = 0; pass < 2; ++pass) {
;     float w[31];
; #pragma unroll
;     for (int k = 0; k < 31; ++k) w[k] = p.w_dw[k * 512 + c0 + pass];
; #pragma unroll
;     for (int tl = 0; tl < 16; ++tl) {
;       float a0 = pass ? bias.y : bias.x;
; #pragma unroll
;       for (int k = 0; k < 31; ++k) a0 += w[k] * (pass ? bfhi(rowv[tl + k]) : bflo(rowv[tl + k]));
;       cs[tl * 520 + c0 + pass] = a0;
;     }
;   }
	v_ashrrev_i32_e32 v7, 31, v6
	v_lshl_add_u64 v[94:95], v[6:7], 2, s[40:41]
	v_add_u32_e32 v6, 0x3800, v4
	v_ashrrev_i32_e32 v7, 31, v6
	v_lshl_add_u64 v[96:97], v[6:7], 2, s[40:41]
	v_add_u32_e32 v6, 0x3a00, v4
	v_ashrrev_i32_e32 v7, 31, v6
	v_lshl_add_u64 v[98:99], v[6:7], 2, s[40:41]
	v_add_u32_e32 v6, 0x3c00, v4
	v_lshl_add_u64 v[10:11], v[4:5], 2, s[40:41]
	v_ashrrev_i32_e32 v7, 31, v6
	v_lshl_add_u64 v[172:173], v[6:7], 2, s[40:41]
	s_nop 0
	s_nop 0
	s_nop 0
	s_nop 0
	s_nop 0
	s_nop 0
	s_nop 0
	s_nop 0
	s_nop 0
	s_nop 0
	s_nop 0
	s_nop 0
	s_nop 0
	s_nop 0
	s_nop 0
	s_nop 0
	s_nop 0
	s_nop 0
	s_nop 0
	s_nop 0
	s_nop 0
	s_nop 0
	s_nop 0
	s_nop 0
	s_nop 0
	s_nop 0
	s_nop 0
	s_nop 0
	s_nop 0
	s_nop 0
	s_nop 0
	s_nop 0
	s_nop 0
	s_nop 0
	s_nop 0
	s_nop 0
	s_nop 0
	s_nop 0
	s_nop 0
	s_nop 0
	s_nop 0
	s_nop 0
	s_nop 0
	s_nop 0
	s_nop 0
	s_nop 0
	s_nop 0
	s_nop 0
	s_nop 0
	s_nop 0
	s_nop 0
	s_nop 0
	s_nop 0
	s_nop 0
	s_nop 0
	s_nop 0
	s_nop 0
	s_nop 0
	s_nop 0
	s_nop 0
	v_and_b32_e32 v175, 0xffff0000, v25
	v_lshlrev_b32_e32 v154, 16, v29
	v_and_b32_e32 v155, 0xffff0000, v29
	v_lshlrev_b32_e32 v152, 16, v27
	v_and_b32_e32 v153, 0xffff0000, v27
	v_lshlrev_b32_e32 v150, 16, v55
	v_and_b32_e32 v151, 0xffff0000, v55
	v_lshlrev_b32_e32 v148, 16, v49
	v_and_b32_e32 v149, 0xffff0000, v49
	v_lshlrev_b32_e32 v144, 16, v59
	v_and_b32_e32 v145, 0xffff0000, v59
	v_lshlrev_b32_e32 v140, 16, v57
	v_and_b32_e32 v141, 0xffff0000, v57
	v_lshlrev_b32_e32 v146, 16, v63
	v_and_b32_e32 v147, 0xffff0000, v63
	v_lshlrev_b32_e32 v142, 16, v61
	v_and_b32_e32 v143, 0xffff0000, v61
	v_lshlrev_b32_e32 v138, 16, v67
	v_and_b32_e32 v139, 0xffff0000, v67
	v_lshlrev_b32_e32 v136, 16, v65
	v_and_b32_e32 v137, 0xffff0000, v65
	v_lshlrev_b32_e32 v134, 16, v71
	v_and_b32_e32 v135, 0xffff0000, v71
	v_lshlrev_b32_e32 v100, 16, v69
	v_and_b32_e32 v101, 0xffff0000, v69
	v_lshlrev_b32_e32 v78, 16, v73
	v_and_b32_e32 v79, 0xffff0000, v73
	v_lshlrev_b32_e32 v48, 16, v75
	v_and_b32_e32 v49, 0xffff0000, v75
	v_lshlrev_b32_e32 v28, 16, v115
	v_and_b32_e32 v29, 0xffff0000, v115
	v_lshlrev_b32_e32 v26, 16, v113
	v_and_b32_e32 v27, 0xffff0000, v113
	v_lshlrev_b32_e32 v24, 16, v121
	v_and_b32_e32 v25, 0xffff0000, v121
	v_lshlrev_b32_e32 v74, 16, v119
	v_and_b32_e32 v75, 0xffff0000, v119
	v_lshlrev_b32_e32 v72, 16, v125
	v_and_b32_e32 v73, 0xffff0000, v125
	v_lshlrev_b32_e32 v70, 16, v123
	v_and_b32_e32 v71, 0xffff0000, v123
	v_lshlrev_b32_e32 v68, 16, v129
	v_and_b32_e32 v69, 0xffff0000, v129
	v_lshlrev_b32_e32 v66, 16, v127
	v_and_b32_e32 v67, 0xffff0000, v127
	v_lshlrev_b32_e32 v64, 16, v133
	v_and_b32_e32 v65, 0xffff0000, v133
	v_lshlrev_b32_e32 v62, 16, v131
	v_and_b32_e32 v63, 0xffff0000, v131
	v_lshlrev_b32_e32 v60, 16, v164
	v_and_b32_e32 v61, 0xffff0000, v164
	v_lshlrev_b32_e32 v58, 16, v163
	v_and_b32_e32 v59, 0xffff0000, v163
	v_lshlrev_b32_e32 v56, 16, v167
	v_and_b32_e32 v57, 0xffff0000, v167
	v_lshlrev_b32_e32 v54, 16, v166
	v_and_b32_e32 v55, 0xffff0000, v166
	v_lshlrev_b32_e32 v124, 16, v169
	v_and_b32_e32 v125, 0xffff0000, v169
	s_waitcnt vmcnt(46)
	v_lshlrev_b32_e32 v122, 16, v171
	v_and_b32_e32 v123, 0xffff0000, v171
	s_waitcnt vmcnt(45)
	v_lshlrev_b32_e32 v132, 16, v170
	v_and_b32_e32 v133, 0xffff0000, v170
	s_waitcnt vmcnt(44)
	v_lshlrev_b32_e32 v130, 16, v168
	v_and_b32_e32 v131, 0xffff0000, v168
	s_waitcnt vmcnt(43)
	v_lshlrev_b32_e32 v128, 16, v165
	v_and_b32_e32 v129, 0xffff0000, v165
	s_waitcnt vmcnt(42)
	v_lshlrev_b32_e32 v126, 16, v162
	s_waitcnt vmcnt(30)
	v_pk_fma_f32 v[174:175], v[176:177], v[174:175], v[2:3]
	v_and_b32_e32 v127, 0xffff0000, v162
	s_waitcnt vmcnt(29)
	v_pk_fma_f32 v[174:175], v[178:179], v[154:155], v[174:175]
	v_pk_fma_f32 v[154:155], v[176:177], v[154:155], v[2:3]
	s_waitcnt vmcnt(28)
	v_pk_fma_f32 v[174:175], v[180:181], v[152:153], v[174:175]
	v_pk_fma_f32 v[154:155], v[178:179], v[152:153], v[154:155]
	v_pk_fma_f32 v[152:153], v[176:177], v[152:153], v[2:3]
	s_waitcnt vmcnt(27)
	v_pk_fma_f32 v[174:175], v[182:183], v[150:151], v[174:175]
	v_pk_fma_f32 v[154:155], v[180:181], v[150:151], v[154:155]
	v_pk_fma_f32 v[152:153], v[178:179], v[150:151], v[152:153]
	v_pk_fma_f32 v[150:151], v[176:177], v[150:151], v[2:3]
	s_waitcnt vmcnt(26)
	v_pk_fma_f32 v[174:175], v[184:185], v[148:149], v[174:175]
	v_pk_fma_f32 v[154:155], v[182:183], v[148:149], v[154:155]
	v_pk_fma_f32 v[152:153], v[180:181], v[148:149], v[152:153]
	v_pk_fma_f32 v[150:151], v[178:179], v[148:149], v[150:151]
	v_pk_fma_f32 v[148:149], v[176:177], v[148:149], v[2:3]
	s_waitcnt vmcnt(25)
	v_pk_fma_f32 v[174:175], v[186:187], v[144:145], v[174:175]
	v_pk_fma_f32 v[154:155], v[184:185], v[144:145], v[154:155]
	v_pk_fma_f32 v[152:153], v[182:183], v[144:145], v[152:153]
	v_pk_fma_f32 v[150:151], v[180:181], v[144:145], v[150:151]
	v_pk_fma_f32 v[148:149], v[178:179], v[144:145], v[148:149]
	v_pk_fma_f32 v[144:145], v[176:177], v[144:145], v[2:3]
	s_waitcnt vmcnt(24)
	v_pk_fma_f32 v[174:175], v[188:189], v[140:141], v[174:175]
	v_pk_fma_f32 v[154:155], v[186:187], v[140:141], v[154:155]
	v_pk_fma_f32 v[152:153], v[184:185], v[140:141], v[152:153]
	v_pk_fma_f32 v[150:151], v[182:183], v[140:141], v[150:151]
	v_pk_fma_f32 v[148:149], v[180:181], v[140:141], v[148:149]
	v_pk_fma_f32 v[144:145], v[178:179], v[140:141], v[144:145]
	v_pk_fma_f32 v[140:141], v[176:177], v[140:141], v[2:3]
	v_lshlrev_b32_e32 v120, 16, v161
	v_pk_fma_f32 v[140:141], v[178:179], v[146:147], v[140:141]
	v_and_b32_e32 v121, 0xffff0000, v161
	v_pk_fma_f32 v[140:141], v[180:181], v[142:143], v[140:141]
	v_lshlrev_b32_e32 v118, 16, v160
	v_pk_fma_f32 v[140:141], v[182:183], v[138:139], v[140:141]
	v_and_b32_e32 v119, 0xffff0000, v160
	v_pk_fma_f32 v[140:141], v[184:185], v[136:137], v[140:141]
	v_lshl_add_u32 v172, v4, 2, s33
	v_pk_fma_f32 v[140:141], v[186:187], v[134:135], v[140:141]
	v_lshlrev_b32_e32 v116, 16, v117
	v_pk_fma_f32 v[140:141], v[188:189], v[100:101], v[140:141]
	v_and_b32_e32 v117, 0xffff0000, v117
	s_waitcnt vmcnt(23)
; DI float bflo(unsigned u) { return __uint_as_float(u << 16); }
; DI float bfhi(unsigned u) { return __uint_as_float(u & 0xffff0000u); }
; DI void conv_item(const Params& p, int item, char* smem) {
;     ...
;   for (int pass = 0; pass < 2; ++pass) {
;     float w[31];
; #pragma unroll
;     for (int k = 0; k < 31; ++k) w[k] = p.w_dw[k * 512 + c0 + pass];
; #pragma unroll
;     for (int tl = 0; tl < 16; ++tl) {
;       float a0 = pass ? bias.y : bias.x;
; #pragma unroll
;       for (int k = 0; k < 31; ++k) a0 += w[k] * (pass ? bfhi(rowv[tl + k]) : bflo(rowv[tl + k]));
;       cs[tl * 520 + c0 + pass] = a0;
;     }
;   }
	v_pk_fma_f32 v[140:141], v[190:191], v[78:79], v[140:141]
	v_pk_fma_f32 v[174:175], v[190:191], v[146:147], v[174:175]
	s_waitcnt vmcnt(22)
	v_pk_fma_f32 v[140:141], v[192:193], v[48:49], v[140:141]
	v_pk_fma_f32 v[154:155], v[188:189], v[146:147], v[154:155]
	s_waitcnt vmcnt(21)
	v_pk_fma_f32 v[140:141], v[194:195], v[28:29], v[140:141]
	v_pk_fma_f32 v[152:153], v[186:187], v[146:147], v[152:153]
	s_waitcnt vmcnt(20)
	v_pk_fma_f32 v[140:141], v[196:197], v[26:27], v[140:141]
	v_pk_fma_f32 v[150:151], v[184:185], v[146:147], v[150:151]
	s_waitcnt vmcnt(19)
	v_pk_fma_f32 v[140:141], v[198:199], v[24:25], v[140:141]
	v_pk_fma_f32 v[148:149], v[182:183], v[146:147], v[148:149]
	s_waitcnt vmcnt(18)
	v_pk_fma_f32 v[140:141], v[200:201], v[74:75], v[140:141]
	v_pk_fma_f32 v[144:145], v[180:181], v[146:147], v[144:145]
	s_waitcnt vmcnt(17)
	v_pk_fma_f32 v[140:141], v[202:203], v[72:73], v[140:141]
	v_pk_fma_f32 v[174:175], v[192:193], v[142:143], v[174:175]
	s_waitcnt vmcnt(16)
	v_pk_fma_f32 v[140:141], v[204:205], v[70:71], v[140:141]
	v_pk_fma_f32 v[154:155], v[190:191], v[142:143], v[154:155]
	s_waitcnt vmcnt(15)
	v_pk_fma_f32 v[140:141], v[206:207], v[68:69], v[140:141]
	v_pk_fma_f32 v[152:153], v[188:189], v[142:143], v[152:153]
	s_waitcnt vmcnt(14)
	v_pk_fma_f32 v[140:141], v[208:209], v[66:67], v[140:141]
	v_pk_fma_f32 v[150:151], v[186:187], v[142:143], v[150:151]
	s_waitcnt vmcnt(13)
	v_pk_fma_f32 v[140:141], v[214:215], v[64:65], v[140:141]
	v_pk_fma_f32 v[148:149], v[184:185], v[142:143], v[148:149]
	s_waitcnt vmcnt(12)
	v_pk_fma_f32 v[140:141], v[216:217], v[62:63], v[140:141]
	v_pk_fma_f32 v[144:145], v[182:183], v[142:143], v[144:145]
	s_waitcnt vmcnt(11)
	v_pk_fma_f32 v[140:141], v[218:219], v[60:61], v[140:141]
	v_pk_fma_f32 v[174:175], v[194:195], v[138:139], v[174:175]
	s_waitcnt vmcnt(10)
	v_pk_fma_f32 v[140:141], v[220:221], v[58:59], v[140:141]
	v_pk_fma_f32 v[154:155], v[192:193], v[138:139], v[154:155]
	s_waitcnt vmcnt(9)
	v_pk_fma_f32 v[140:141], v[222:223], v[56:57], v[140:141]
	v_pk_fma_f32 v[152:153], v[190:191], v[138:139], v[152:153]
	s_waitcnt vmcnt(8)
	v_pk_fma_f32 v[140:141], v[224:225], v[54:55], v[140:141]
	v_pk_fma_f32 v[150:151], v[188:189], v[138:139], v[150:151]
	s_waitcnt vmcnt(7)
	v_pk_fma_f32 v[140:141], v[226:227], v[124:125], v[140:141]
	v_pk_fma_f32 v[148:149], v[186:187], v[138:139], v[148:149]
	s_waitcnt vmcnt(6)
	v_pk_fma_f32 v[140:141], v[228:229], v[122:123], v[140:141]
	v_pk_fma_f32 v[144:145], v[184:185], v[138:139], v[144:145]
	s_waitcnt vmcnt(5)
	v_pk_fma_f32 v[140:141], v[230:231], v[132:133], v[140:141]
	v_pk_fma_f32 v[174:175], v[196:197], v[136:137], v[174:175]
	s_waitcnt vmcnt(4)
	v_pk_fma_f32 v[140:141], v[232:233], v[130:131], v[140:141]
	v_pk_fma_f32 v[154:155], v[194:195], v[136:137], v[154:155]
	s_waitcnt vmcnt(3)
	v_pk_fma_f32 v[140:141], v[234:235], v[128:129], v[140:141]
	v_pk_fma_f32 v[152:153], v[192:193], v[136:137], v[152:153]
	s_waitcnt vmcnt(2)
	v_pk_fma_f32 v[140:141], v[236:237], v[126:127], v[140:141]
	v_pk_fma_f32 v[150:151], v[190:191], v[136:137], v[150:151]
	s_waitcnt vmcnt(1)
	v_pk_fma_f32 v[140:141], v[238:239], v[120:121], v[140:141]
	v_pk_fma_f32 v[148:149], v[188:189], v[136:137], v[148:149]
	s_waitcnt vmcnt(0)
	v_pk_fma_f32 v[140:141], v[240:241], v[118:119], v[140:141]
	ds_write_b64 v172, v[140:141] offset:12480
	v_pk_fma_f32 v[140:141], v[176:177], v[146:147], v[2:3]
	v_pk_fma_f32 v[144:145], v[186:187], v[136:137], v[144:145]
	v_pk_fma_f32 v[140:141], v[178:179], v[142:143], v[140:141]
	v_pk_fma_f32 v[174:175], v[198:199], v[134:135], v[174:175]
	v_pk_fma_f32 v[140:141], v[180:181], v[138:139], v[140:141]
	v_pk_fma_f32 v[154:155], v[196:197], v[134:135], v[154:155]
	v_pk_fma_f32 v[140:141], v[182:183], v[136:137], v[140:141]
	v_pk_fma_f32 v[152:153], v[194:195], v[134:135], v[152:153]
	v_pk_fma_f32 v[140:141], v[184:185], v[134:135], v[140:141]
	v_pk_fma_f32 v[150:151], v[192:193], v[134:135], v[150:151]
	v_pk_fma_f32 v[140:141], v[186:187], v[100:101], v[140:141]
	v_pk_fma_f32 v[148:149], v[190:191], v[134:135], v[148:149]
	v_pk_fma_f32 v[140:141], v[188:189], v[78:79], v[140:141]
	v_pk_fma_f32 v[144:145], v[188:189], v[134:135], v[144:145]
	v_pk_fma_f32 v[140:141], v[190:191], v[48:49], v[140:141]
	v_pk_fma_f32 v[174:175], v[200:201], v[100:101], v[174:175]
	v_pk_fma_f32 v[140:141], v[192:193], v[28:29], v[140:141]
	v_pk_fma_f32 v[154:155], v[198:199], v[100:101], v[154:155]
	v_pk_fma_f32 v[140:141], v[194:195], v[26:27], v[140:141]
	v_pk_fma_f32 v[152:153], v[196:197], v[100:101], v[152:153]
	v_pk_fma_f32 v[140:141], v[196:197], v[24:25], v[140:141]
	v_pk_fma_f32 v[150:151], v[194:195], v[100:101], v[150:151]
	v_pk_fma_f32 v[140:141], v[198:199], v[74:75], v[140:141]
	v_pk_fma_f32 v[148:149], v[192:193], v[100:101], v[148:149]
	v_pk_fma_f32 v[140:141], v[200:201], v[72:73], v[140:141]
	v_pk_fma_f32 v[144:145], v[190:191], v[100:101], v[144:145]
	v_pk_fma_f32 v[140:141], v[202:203], v[70:71], v[140:141]
	v_pk_fma_f32 v[174:175], v[202:203], v[78:79], v[174:175]
	v_pk_fma_f32 v[140:141], v[204:205], v[68:69], v[140:141]
	v_pk_fma_f32 v[154:155], v[200:201], v[78:79], v[154:155]
	v_pk_fma_f32 v[140:141], v[206:207], v[66:67], v[140:141]
	v_pk_fma_f32 v[152:153], v[198:199], v[78:79], v[152:153]
	v_pk_fma_f32 v[140:141], v[208:209], v[64:65], v[140:141]
	v_pk_fma_f32 v[150:151], v[196:197], v[78:79], v[150:151]
	v_pk_fma_f32 v[140:141], v[214:215], v[62:63], v[140:141]
	v_pk_fma_f32 v[148:149], v[194:195], v[78:79], v[148:149]
	v_pk_fma_f32 v[140:141], v[216:217], v[60:61], v[140:141]
	v_pk_fma_f32 v[144:145], v[192:193], v[78:79], v[144:145]
; DI float bflo(unsigned u) { return __uint_as_float(u << 16); }
; DI float bfhi(unsigned u) { return __uint_as_float(u & 0xffff0000u); }
; DI void conv_item(const Params& p, int item, char* smem) {
;     ...
;   for (int pass = 0; pass < 2; ++pass) {
;     float w[31];
; #pragma unroll
;     for (int k = 0; k < 31; ++k) w[k] = p.w_dw[k * 512 + c0 + pass];
; #pragma unroll
;     for (int tl = 0; tl < 16; ++tl) {
;       float a0 = pass ? bias.y : bias.x;
; #pragma unroll
;       for (int k = 0; k < 31; ++k) a0 += w[k] * (pass ? bfhi(rowv[tl + k]) : bflo(rowv[tl + k]));
;       cs[tl * 520 + c0 + pass] = a0;
;     }
;   }
	v_pk_fma_f32 v[140:141], v[218:219], v[58:59], v[140:141]
	v_pk_fma_f32 v[174:175], v[204:205], v[48:49], v[174:175]
	v_pk_fma_f32 v[140:141], v[220:221], v[56:57], v[140:141]
	v_pk_fma_f32 v[154:155], v[202:203], v[48:49], v[154:155]
	v_pk_fma_f32 v[140:141], v[222:223], v[54:55], v[140:141]
	v_pk_fma_f32 v[152:153], v[200:201], v[48:49], v[152:153]
	v_pk_fma_f32 v[140:141], v[224:225], v[124:125], v[140:141]
	v_pk_fma_f32 v[150:151], v[198:199], v[48:49], v[150:151]
	v_pk_fma_f32 v[140:141], v[226:227], v[122:123], v[140:141]
	v_pk_fma_f32 v[148:149], v[196:197], v[48:49], v[148:149]
	v_pk_fma_f32 v[140:141], v[228:229], v[132:133], v[140:141]
	v_pk_fma_f32 v[144:145], v[194:195], v[48:49], v[144:145]
	v_pk_fma_f32 v[140:141], v[230:231], v[130:131], v[140:141]
	v_pk_fma_f32 v[144:145], v[196:197], v[28:29], v[144:145]
	v_pk_fma_f32 v[140:141], v[232:233], v[128:129], v[140:141]
	v_pk_fma_f32 v[148:149], v[198:199], v[28:29], v[148:149]
	v_pk_fma_f32 v[140:141], v[234:235], v[126:127], v[140:141]
	v_pk_fma_f32 v[144:145], v[198:199], v[26:27], v[144:145]
	v_pk_fma_f32 v[140:141], v[236:237], v[120:121], v[140:141]
	v_pk_fma_f32 v[150:151], v[200:201], v[28:29], v[150:151]
	v_pk_fma_f32 v[140:141], v[238:239], v[118:119], v[140:141]
	v_pk_fma_f32 v[148:149], v[200:201], v[26:27], v[148:149]
	v_pk_fma_f32 v[140:141], v[240:241], v[116:117], v[140:141]
	ds_write_b64 v172, v[140:141] offset:14560
	v_pk_fma_f32 v[140:141], v[176:177], v[142:143], v[2:3]
	v_pk_fma_f32 v[144:145], v[200:201], v[24:25], v[144:145]
	v_pk_fma_f32 v[140:141], v[178:179], v[138:139], v[140:141]
	v_pk_fma_f32 v[138:139], v[176:177], v[138:139], v[2:3]
	v_pk_fma_f32 v[140:141], v[180:181], v[136:137], v[140:141]
	v_pk_fma_f32 v[138:139], v[178:179], v[136:137], v[138:139]
	v_pk_fma_f32 v[136:137], v[176:177], v[136:137], v[2:3]
	v_pk_fma_f32 v[140:141], v[182:183], v[134:135], v[140:141]
	v_pk_fma_f32 v[138:139], v[180:181], v[134:135], v[138:139]
	v_pk_fma_f32 v[136:137], v[178:179], v[134:135], v[136:137]
	v_pk_fma_f32 v[134:135], v[176:177], v[134:135], v[2:3]
	v_pk_fma_f32 v[140:141], v[184:185], v[100:101], v[140:141]
	v_pk_fma_f32 v[138:139], v[182:183], v[100:101], v[138:139]
	v_pk_fma_f32 v[136:137], v[180:181], v[100:101], v[136:137]
	v_pk_fma_f32 v[134:135], v[178:179], v[100:101], v[134:135]
	v_pk_fma_f32 v[100:101], v[176:177], v[100:101], v[2:3]
	v_pk_fma_f32 v[140:141], v[186:187], v[78:79], v[140:141]
	v_pk_fma_f32 v[138:139], v[184:185], v[78:79], v[138:139]
	v_pk_fma_f32 v[136:137], v[182:183], v[78:79], v[136:137]
	v_pk_fma_f32 v[134:135], v[180:181], v[78:79], v[134:135]
	v_pk_fma_f32 v[100:101], v[178:179], v[78:79], v[100:101]
	v_pk_fma_f32 v[78:79], v[176:177], v[78:79], v[2:3]
	v_pk_fma_f32 v[140:141], v[188:189], v[48:49], v[140:141]
	v_pk_fma_f32 v[138:139], v[186:187], v[48:49], v[138:139]
	v_pk_fma_f32 v[136:137], v[184:185], v[48:49], v[136:137]
	v_pk_fma_f32 v[134:135], v[182:183], v[48:49], v[134:135]
	v_pk_fma_f32 v[100:101], v[180:181], v[48:49], v[100:101]
	v_pk_fma_f32 v[78:79], v[178:179], v[48:49], v[78:79]
	v_pk_fma_f32 v[48:49], v[176:177], v[48:49], v[2:3]
	v_pk_fma_f32 v[2:3], v[176:177], v[28:29], v[2:3]
	v_pk_fma_f32 v[48:49], v[178:179], v[28:29], v[48:49]
	v_pk_fma_f32 v[2:3], v[178:179], v[26:27], v[2:3]
	v_pk_fma_f32 v[78:79], v[180:181], v[28:29], v[78:79]
	v_pk_fma_f32 v[48:49], v[180:181], v[26:27], v[48:49]
	v_pk_fma_f32 v[2:3], v[180:181], v[24:25], v[2:3]
	v_pk_fma_f32 v[100:101], v[182:183], v[28:29], v[100:101]
	v_pk_fma_f32 v[78:79], v[182:183], v[26:27], v[78:79]
	v_pk_fma_f32 v[48:49], v[182:183], v[24:25], v[48:49]
	v_pk_fma_f32 v[2:3], v[182:183], v[74:75], v[2:3]
	v_pk_fma_f32 v[134:135], v[184:185], v[28:29], v[134:135]
	v_pk_fma_f32 v[100:101], v[184:185], v[26:27], v[100:101]
	v_pk_fma_f32 v[78:79], v[184:185], v[24:25], v[78:79]
	v_pk_fma_f32 v[48:49], v[184:185], v[74:75], v[48:49]
	v_pk_fma_f32 v[2:3], v[184:185], v[72:73], v[2:3]
	v_pk_fma_f32 v[136:137], v[186:187], v[28:29], v[136:137]
	v_pk_fma_f32 v[134:135], v[186:187], v[26:27], v[134:135]
	v_pk_fma_f32 v[100:101], v[186:187], v[24:25], v[100:101]
	v_pk_fma_f32 v[78:79], v[186:187], v[74:75], v[78:79]
	v_pk_fma_f32 v[48:49], v[186:187], v[72:73], v[48:49]
	v_pk_fma_f32 v[2:3], v[186:187], v[70:71], v[2:3]
	v_pk_fma_f32 v[138:139], v[188:189], v[28:29], v[138:139]
	v_pk_fma_f32 v[136:137], v[188:189], v[26:27], v[136:137]
	v_pk_fma_f32 v[134:135], v[188:189], v[24:25], v[134:135]
	v_pk_fma_f32 v[100:101], v[188:189], v[74:75], v[100:101]
	v_pk_fma_f32 v[78:79], v[188:189], v[72:73], v[78:79]
	v_pk_fma_f32 v[48:49], v[188:189], v[70:71], v[48:49]
	v_pk_fma_f32 v[2:3], v[188:189], v[68:69], v[2:3]
	v_pk_fma_f32 v[140:141], v[190:191], v[28:29], v[140:141]
	v_pk_fma_f32 v[138:139], v[190:191], v[26:27], v[138:139]
	v_pk_fma_f32 v[136:137], v[190:191], v[24:25], v[136:137]
	v_pk_fma_f32 v[134:135], v[190:191], v[74:75], v[134:135]
	v_pk_fma_f32 v[100:101], v[190:191], v[72:73], v[100:101]
	v_pk_fma_f32 v[78:79], v[190:191], v[70:71], v[78:79]
	v_pk_fma_f32 v[48:49], v[190:191], v[68:69], v[48:49]
	v_pk_fma_f32 v[2:3], v[190:191], v[66:67], v[2:3]
	v_pk_fma_f32 v[140:141], v[192:193], v[26:27], v[140:141]
	v_pk_fma_f32 v[138:139], v[192:193], v[24:25], v[138:139]
	v_pk_fma_f32 v[136:137], v[192:193], v[74:75], v[136:137]
	v_pk_fma_f32 v[134:135], v[192:193], v[72:73], v[134:135]
	v_pk_fma_f32 v[100:101], v[192:193], v[70:71], v[100:101]
	v_pk_fma_f32 v[78:79], v[192:193], v[68:69], v[78:79]
	v_pk_fma_f32 v[48:49], v[192:193], v[66:67], v[48:49]
	v_pk_fma_f32 v[2:3], v[192:193], v[64:65], v[2:3]
	v_pk_fma_f32 v[140:141], v[194:195], v[24:25], v[140:141]
; DI float bflo(unsigned u) { return __uint_as_float(u << 16); }
; DI float bfhi(unsigned u) { return __uint_as_float(u & 0xffff0000u); }
; DI void conv_item(const Params& p, int item, char* smem) {
;     ...
;   for (int pass = 0; pass < 2; ++pass) {
;     float w[31];
; #pragma unroll
;     for (int k = 0; k < 31; ++k) w[k] = p.w_dw[k * 512 + c0 + pass];
; #pragma unroll
;     for (int tl = 0; tl < 16; ++tl) {
;       float a0 = pass ? bias.y : bias.x;
; #pragma unroll
;       for (int k = 0; k < 31; ++k) a0 += w[k] * (pass ? bfhi(rowv[tl + k]) : bflo(rowv[tl + k]));
;       cs[tl * 520 + c0 + pass] = a0;
;     }
;   }
	v_pk_fma_f32 v[138:139], v[194:195], v[74:75], v[138:139]
	v_pk_fma_f32 v[136:137], v[194:195], v[72:73], v[136:137]
	v_pk_fma_f32 v[134:135], v[194:195], v[70:71], v[134:135]
	v_pk_fma_f32 v[100:101], v[194:195], v[68:69], v[100:101]
	v_pk_fma_f32 v[78:79], v[194:195], v[66:67], v[78:79]
	v_pk_fma_f32 v[48:49], v[194:195], v[64:65], v[48:49]
	v_pk_fma_f32 v[2:3], v[194:195], v[62:63], v[2:3]
	v_pk_fma_f32 v[140:141], v[196:197], v[74:75], v[140:141]
	v_pk_fma_f32 v[138:139], v[196:197], v[72:73], v[138:139]
	v_pk_fma_f32 v[136:137], v[196:197], v[70:71], v[136:137]
	v_pk_fma_f32 v[134:135], v[196:197], v[68:69], v[134:135]
	v_pk_fma_f32 v[100:101], v[196:197], v[66:67], v[100:101]
	v_pk_fma_f32 v[78:79], v[196:197], v[64:65], v[78:79]
	v_pk_fma_f32 v[48:49], v[196:197], v[62:63], v[48:49]
	v_pk_fma_f32 v[2:3], v[196:197], v[60:61], v[2:3]
	v_pk_fma_f32 v[140:141], v[198:199], v[72:73], v[140:141]
	v_pk_fma_f32 v[138:139], v[198:199], v[70:71], v[138:139]
	v_pk_fma_f32 v[136:137], v[198:199], v[68:69], v[136:137]
	v_pk_fma_f32 v[134:135], v[198:199], v[66:67], v[134:135]
	v_pk_fma_f32 v[100:101], v[198:199], v[64:65], v[100:101]
	v_pk_fma_f32 v[78:79], v[198:199], v[62:63], v[78:79]
	v_pk_fma_f32 v[48:49], v[198:199], v[60:61], v[48:49]
	v_pk_fma_f32 v[2:3], v[198:199], v[58:59], v[2:3]
	v_pk_fma_f32 v[140:141], v[200:201], v[70:71], v[140:141]
	v_pk_fma_f32 v[138:139], v[200:201], v[68:69], v[138:139]
	v_pk_fma_f32 v[136:137], v[200:201], v[66:67], v[136:137]
	v_pk_fma_f32 v[134:135], v[200:201], v[64:65], v[134:135]
	v_pk_fma_f32 v[100:101], v[200:201], v[62:63], v[100:101]
	v_pk_fma_f32 v[78:79], v[200:201], v[60:61], v[78:79]
	v_pk_fma_f32 v[48:49], v[200:201], v[58:59], v[48:49]
	v_pk_fma_f32 v[2:3], v[200:201], v[56:57], v[2:3]
	v_pk_fma_f32 v[152:153], v[202:203], v[28:29], v[152:153]
	v_pk_fma_f32 v[150:151], v[202:203], v[26:27], v[150:151]
	v_pk_fma_f32 v[148:149], v[202:203], v[24:25], v[148:149]
	v_pk_fma_f32 v[144:145], v[202:203], v[74:75], v[144:145]
	v_pk_fma_f32 v[140:141], v[202:203], v[68:69], v[140:141]
	v_pk_fma_f32 v[138:139], v[202:203], v[66:67], v[138:139]
	v_pk_fma_f32 v[136:137], v[202:203], v[64:65], v[136:137]
	v_pk_fma_f32 v[134:135], v[202:203], v[62:63], v[134:135]
	v_pk_fma_f32 v[100:101], v[202:203], v[60:61], v[100:101]
	v_pk_fma_f32 v[78:79], v[202:203], v[58:59], v[78:79]
	v_pk_fma_f32 v[48:49], v[202:203], v[56:57], v[48:49]
	v_pk_fma_f32 v[2:3], v[202:203], v[54:55], v[2:3]
	v_pk_fma_f32 v[154:155], v[204:205], v[28:29], v[154:155]
	v_pk_fma_f32 v[152:153], v[204:205], v[26:27], v[152:153]
	v_pk_fma_f32 v[150:151], v[204:205], v[24:25], v[150:151]
	v_pk_fma_f32 v[148:149], v[204:205], v[74:75], v[148:149]
	v_pk_fma_f32 v[144:145], v[204:205], v[72:73], v[144:145]
	v_pk_fma_f32 v[140:141], v[204:205], v[66:67], v[140:141]
	v_pk_fma_f32 v[138:139], v[204:205], v[64:65], v[138:139]
	v_pk_fma_f32 v[136:137], v[204:205], v[62:63], v[136:137]
	v_pk_fma_f32 v[134:135], v[204:205], v[60:61], v[134:135]
	v_pk_fma_f32 v[100:101], v[204:205], v[58:59], v[100:101]
	v_pk_fma_f32 v[78:79], v[204:205], v[56:57], v[78:79]
	v_pk_fma_f32 v[48:49], v[204:205], v[54:55], v[48:49]
	v_pk_fma_f32 v[2:3], v[204:205], v[124:125], v[2:3]
	v_pk_fma_f32 v[174:175], v[206:207], v[28:29], v[174:175]
	v_pk_fma_f32 v[154:155], v[206:207], v[26:27], v[154:155]
	v_pk_fma_f32 v[152:153], v[206:207], v[24:25], v[152:153]
	v_pk_fma_f32 v[150:151], v[206:207], v[74:75], v[150:151]
	v_pk_fma_f32 v[148:149], v[206:207], v[72:73], v[148:149]
	v_pk_fma_f32 v[144:145], v[206:207], v[70:71], v[144:145]
	v_pk_fma_f32 v[140:141], v[206:207], v[64:65], v[140:141]
	v_pk_fma_f32 v[138:139], v[206:207], v[62:63], v[138:139]
	v_pk_fma_f32 v[136:137], v[206:207], v[60:61], v[136:137]
	v_pk_fma_f32 v[134:135], v[206:207], v[58:59], v[134:135]
	v_pk_fma_f32 v[100:101], v[206:207], v[56:57], v[100:101]
	v_pk_fma_f32 v[78:79], v[206:207], v[54:55], v[78:79]
	v_pk_fma_f32 v[48:49], v[206:207], v[124:125], v[48:49]
	v_pk_fma_f32 v[2:3], v[206:207], v[122:123], v[2:3]
	v_pk_fma_f32 v[174:175], v[208:209], v[26:27], v[174:175]
	v_pk_fma_f32 v[154:155], v[208:209], v[24:25], v[154:155]
	v_pk_fma_f32 v[152:153], v[208:209], v[74:75], v[152:153]
	v_pk_fma_f32 v[150:151], v[208:209], v[72:73], v[150:151]
	v_pk_fma_f32 v[148:149], v[208:209], v[70:71], v[148:149]
	v_pk_fma_f32 v[144:145], v[208:209], v[68:69], v[144:145]
	v_pk_fma_f32 v[140:141], v[208:209], v[62:63], v[140:141]
	v_pk_fma_f32 v[138:139], v[208:209], v[60:61], v[138:139]
	v_pk_fma_f32 v[136:137], v[208:209], v[58:59], v[136:137]
	v_pk_fma_f32 v[134:135], v[208:209], v[56:57], v[134:135]
	v_pk_fma_f32 v[100:101], v[208:209], v[54:55], v[100:101]
	v_pk_fma_f32 v[78:79], v[208:209], v[124:125], v[78:79]
	v_pk_fma_f32 v[48:49], v[208:209], v[122:123], v[48:49]
	v_pk_fma_f32 v[2:3], v[208:209], v[132:133], v[2:3]
	v_pk_fma_f32 v[174:175], v[214:215], v[24:25], v[174:175]
	v_pk_fma_f32 v[154:155], v[214:215], v[74:75], v[154:155]
	v_pk_fma_f32 v[152:153], v[214:215], v[72:73], v[152:153]
	v_pk_fma_f32 v[150:151], v[214:215], v[70:71], v[150:151]
	v_pk_fma_f32 v[148:149], v[214:215], v[68:69], v[148:149]
	v_pk_fma_f32 v[144:145], v[214:215], v[66:67], v[144:145]
	v_pk_fma_f32 v[140:141], v[214:215], v[60:61], v[140:141]
	v_pk_fma_f32 v[138:139], v[214:215], v[58:59], v[138:139]
	v_pk_fma_f32 v[136:137], v[214:215], v[56:57], v[136:137]
	v_pk_fma_f32 v[134:135], v[214:215], v[54:55], v[134:135]
	v_pk_fma_f32 v[100:101], v[214:215], v[124:125], v[100:101]
	v_pk_fma_f32 v[78:79], v[214:215], v[122:123], v[78:79]
	v_pk_fma_f32 v[48:49], v[214:215], v[132:133], v[48:49]
	v_pk_fma_f32 v[2:3], v[214:215], v[130:131], v[2:3]
; DI float bflo(unsigned u) { return __uint_as_float(u << 16); }
; DI float bfhi(unsigned u) { return __uint_as_float(u & 0xffff0000u); }
; DI void conv_item(const Params& p, int item, char* smem) {
;     ...
;   for (int pass = 0; pass < 2; ++pass) {
;     float w[31];
; #pragma unroll
;     for (int k = 0; k < 31; ++k) w[k] = p.w_dw[k * 512 + c0 + pass];
; #pragma unroll
;     for (int tl = 0; tl < 16; ++tl) {
;       float a0 = pass ? bias.y : bias.x;
; #pragma unroll
;       for (int k = 0; k < 31; ++k) a0 += w[k] * (pass ? bfhi(rowv[tl + k]) : bflo(rowv[tl + k]));
;       cs[tl * 520 + c0 + pass] = a0;
;     }
;   }
	v_pk_fma_f32 v[174:175], v[216:217], v[74:75], v[174:175]
	v_pk_fma_f32 v[154:155], v[216:217], v[72:73], v[154:155]
	v_pk_fma_f32 v[152:153], v[216:217], v[70:71], v[152:153]
	v_pk_fma_f32 v[150:151], v[216:217], v[68:69], v[150:151]
	v_pk_fma_f32 v[148:149], v[216:217], v[66:67], v[148:149]
	v_pk_fma_f32 v[144:145], v[216:217], v[64:65], v[144:145]
	v_pk_fma_f32 v[140:141], v[216:217], v[58:59], v[140:141]
	v_pk_fma_f32 v[138:139], v[216:217], v[56:57], v[138:139]
	v_pk_fma_f32 v[136:137], v[216:217], v[54:55], v[136:137]
	v_pk_fma_f32 v[134:135], v[216:217], v[124:125], v[134:135]
	v_pk_fma_f32 v[100:101], v[216:217], v[122:123], v[100:101]
	v_pk_fma_f32 v[78:79], v[216:217], v[132:133], v[78:79]
	v_pk_fma_f32 v[48:49], v[216:217], v[130:131], v[48:49]
	v_pk_fma_f32 v[2:3], v[216:217], v[128:129], v[2:3]
	v_pk_fma_f32 v[174:175], v[218:219], v[72:73], v[174:175]
	v_pk_fma_f32 v[154:155], v[218:219], v[70:71], v[154:155]
	v_pk_fma_f32 v[152:153], v[218:219], v[68:69], v[152:153]
	v_pk_fma_f32 v[150:151], v[218:219], v[66:67], v[150:151]
	v_pk_fma_f32 v[148:149], v[218:219], v[64:65], v[148:149]
	v_pk_fma_f32 v[144:145], v[218:219], v[62:63], v[144:145]
	v_pk_fma_f32 v[140:141], v[218:219], v[56:57], v[140:141]
	v_pk_fma_f32 v[138:139], v[218:219], v[54:55], v[138:139]
	v_pk_fma_f32 v[136:137], v[218:219], v[124:125], v[136:137]
	v_pk_fma_f32 v[134:135], v[218:219], v[122:123], v[134:135]
	v_pk_fma_f32 v[100:101], v[218:219], v[132:133], v[100:101]
	v_pk_fma_f32 v[78:79], v[218:219], v[130:131], v[78:79]
	v_pk_fma_f32 v[48:49], v[218:219], v[128:129], v[48:49]
	v_pk_fma_f32 v[2:3], v[218:219], v[126:127], v[2:3]
	v_pk_fma_f32 v[166:167], v[220:221], v[70:71], v[174:175]
	v_pk_fma_f32 v[154:155], v[220:221], v[68:69], v[154:155]
	v_pk_fma_f32 v[152:153], v[220:221], v[66:67], v[152:153]
	v_pk_fma_f32 v[150:151], v[220:221], v[64:65], v[150:151]
	v_pk_fma_f32 v[148:149], v[220:221], v[62:63], v[148:149]
	v_pk_fma_f32 v[144:145], v[220:221], v[60:61], v[144:145]
	v_pk_fma_f32 v[140:141], v[220:221], v[54:55], v[140:141]
	v_pk_fma_f32 v[138:139], v[220:221], v[124:125], v[138:139]
	v_pk_fma_f32 v[136:137], v[220:221], v[122:123], v[136:137]
	v_pk_fma_f32 v[134:135], v[220:221], v[132:133], v[134:135]
	v_pk_fma_f32 v[100:101], v[220:221], v[130:131], v[100:101]
	v_pk_fma_f32 v[78:79], v[220:221], v[128:129], v[78:79]
	v_pk_fma_f32 v[48:49], v[220:221], v[126:127], v[48:49]
	v_pk_fma_f32 v[2:3], v[220:221], v[120:121], v[2:3]
	v_pk_fma_f32 v[166:167], v[222:223], v[68:69], v[166:167]
	v_pk_fma_f32 v[154:155], v[222:223], v[66:67], v[154:155]
	v_pk_fma_f32 v[152:153], v[222:223], v[64:65], v[152:153]
	v_pk_fma_f32 v[150:151], v[222:223], v[62:63], v[150:151]
	v_pk_fma_f32 v[148:149], v[222:223], v[60:61], v[148:149]
	v_pk_fma_f32 v[144:145], v[222:223], v[58:59], v[144:145]
	v_pk_fma_f32 v[140:141], v[222:223], v[124:125], v[140:141]
	v_pk_fma_f32 v[138:139], v[222:223], v[122:123], v[138:139]
	v_pk_fma_f32 v[136:137], v[222:223], v[132:133], v[136:137]
	v_pk_fma_f32 v[134:135], v[222:223], v[130:131], v[134:135]
	v_pk_fma_f32 v[100:101], v[222:223], v[128:129], v[100:101]
	v_pk_fma_f32 v[78:79], v[222:223], v[126:127], v[78:79]
	v_pk_fma_f32 v[48:49], v[222:223], v[120:121], v[48:49]
	v_pk_fma_f32 v[2:3], v[222:223], v[118:119], v[2:3]
	v_lshlrev_b32_e32 v114, 16, v159
	v_pk_fma_f32 v[166:167], v[224:225], v[66:67], v[166:167]
	v_pk_fma_f32 v[154:155], v[224:225], v[64:65], v[154:155]
	v_pk_fma_f32 v[152:153], v[224:225], v[62:63], v[152:153]
	v_pk_fma_f32 v[150:151], v[224:225], v[60:61], v[150:151]
	v_pk_fma_f32 v[148:149], v[224:225], v[58:59], v[148:149]
	v_pk_fma_f32 v[144:145], v[224:225], v[56:57], v[144:145]
	v_and_b32_e32 v115, 0xffff0000, v159
	v_pk_fma_f32 v[140:141], v[224:225], v[122:123], v[140:141]
	v_pk_fma_f32 v[138:139], v[224:225], v[132:133], v[138:139]
	v_pk_fma_f32 v[136:137], v[224:225], v[130:131], v[136:137]
	v_pk_fma_f32 v[134:135], v[224:225], v[128:129], v[134:135]
	v_pk_fma_f32 v[100:101], v[224:225], v[126:127], v[100:101]
	v_pk_fma_f32 v[78:79], v[224:225], v[120:121], v[78:79]
	v_pk_fma_f32 v[48:49], v[224:225], v[118:119], v[48:49]
	v_pk_fma_f32 v[2:3], v[224:225], v[116:117], v[2:3]
	v_lshlrev_b32_e32 v112, 16, v158
	v_pk_fma_f32 v[166:167], v[226:227], v[64:65], v[166:167]
	v_pk_fma_f32 v[154:155], v[226:227], v[62:63], v[154:155]
	v_pk_fma_f32 v[152:153], v[226:227], v[60:61], v[152:153]
	v_pk_fma_f32 v[150:151], v[226:227], v[58:59], v[150:151]
	v_pk_fma_f32 v[148:149], v[226:227], v[56:57], v[148:149]
	v_pk_fma_f32 v[144:145], v[226:227], v[54:55], v[144:145]
	v_pk_fma_f32 v[140:141], v[226:227], v[132:133], v[140:141]
	v_and_b32_e32 v113, 0xffff0000, v158
	v_pk_fma_f32 v[138:139], v[226:227], v[130:131], v[138:139]
	v_pk_fma_f32 v[136:137], v[226:227], v[128:129], v[136:137]
	v_pk_fma_f32 v[134:135], v[226:227], v[126:127], v[134:135]
	v_pk_fma_f32 v[100:101], v[226:227], v[120:121], v[100:101]
	v_pk_fma_f32 v[78:79], v[226:227], v[118:119], v[78:79]
	v_pk_fma_f32 v[48:49], v[226:227], v[116:117], v[48:49]
	v_pk_fma_f32 v[2:3], v[226:227], v[114:115], v[2:3]
	v_lshlrev_b32_e32 v110, 16, v111
	v_pk_fma_f32 v[166:167], v[228:229], v[62:63], v[166:167]
	v_pk_fma_f32 v[154:155], v[228:229], v[60:61], v[154:155]
	v_pk_fma_f32 v[152:153], v[228:229], v[58:59], v[152:153]
	v_pk_fma_f32 v[150:151], v[228:229], v[56:57], v[150:151]
	v_pk_fma_f32 v[148:149], v[228:229], v[54:55], v[148:149]
	v_pk_fma_f32 v[144:145], v[228:229], v[124:125], v[144:145]
	v_pk_fma_f32 v[140:141], v[228:229], v[130:131], v[140:141]
	v_pk_fma_f32 v[138:139], v[228:229], v[128:129], v[138:139]
	v_and_b32_e32 v111, 0xffff0000, v111
; DI void hsync() { hsync_impl(false); }
; DI float bflo(unsigned u) { return __uint_as_float(u << 16); }
; DI float bfhi(unsigned u) { return __uint_as_float(u & 0xffff0000u); }
; DI void conv_item(const Params& p, int item, char* smem) {
;     ...
;   for (int pass = 0; pass < 2; ++pass) {
;     float w[31];
; #pragma unroll
;     for (int k = 0; k < 31; ++k) w[k] = p.w_dw[k * 512 + c0 + pass];
; #pragma unroll
;     for (int tl = 0; tl < 16; ++tl) {
;       float a0 = pass ? bias.y : bias.x;
; #pragma unroll
;       for (int k = 0; k < 31; ++k) a0 += w[k] * (pass ? bfhi(rowv[tl + k]) : bflo(rowv[tl + k]));
;       cs[tl * 520 + c0 + pass] = a0;
;     }
;   }
;   hsync();
	v_pk_fma_f32 v[136:137], v[228:229], v[126:127], v[136:137]
	v_pk_fma_f32 v[134:135], v[228:229], v[120:121], v[134:135]
	v_pk_fma_f32 v[100:101], v[228:229], v[118:119], v[100:101]
	v_pk_fma_f32 v[78:79], v[228:229], v[116:117], v[78:79]
	v_pk_fma_f32 v[48:49], v[228:229], v[114:115], v[48:49]
	v_pk_fma_f32 v[2:3], v[228:229], v[112:113], v[2:3]
	v_lshlrev_b32_e32 v108, 16, v109
	v_pk_fma_f32 v[166:167], v[230:231], v[60:61], v[166:167]
	v_pk_fma_f32 v[154:155], v[230:231], v[58:59], v[154:155]
	v_pk_fma_f32 v[152:153], v[230:231], v[56:57], v[152:153]
	v_pk_fma_f32 v[150:151], v[230:231], v[54:55], v[150:151]
	v_pk_fma_f32 v[148:149], v[230:231], v[124:125], v[148:149]
	v_pk_fma_f32 v[144:145], v[230:231], v[122:123], v[144:145]
	v_pk_fma_f32 v[140:141], v[230:231], v[128:129], v[140:141]
	v_pk_fma_f32 v[138:139], v[230:231], v[126:127], v[138:139]
	v_pk_fma_f32 v[136:137], v[230:231], v[120:121], v[136:137]
	v_and_b32_e32 v109, 0xffff0000, v109
	v_pk_fma_f32 v[134:135], v[230:231], v[118:119], v[134:135]
	v_pk_fma_f32 v[100:101], v[230:231], v[116:117], v[100:101]
	v_pk_fma_f32 v[78:79], v[230:231], v[114:115], v[78:79]
	v_pk_fma_f32 v[48:49], v[230:231], v[112:113], v[48:49]
	v_pk_fma_f32 v[2:3], v[230:231], v[110:111], v[2:3]
	v_lshlrev_b32_e32 v106, 16, v107
	v_pk_fma_f32 v[166:167], v[232:233], v[58:59], v[166:167]
	v_pk_fma_f32 v[154:155], v[232:233], v[56:57], v[154:155]
	v_pk_fma_f32 v[152:153], v[232:233], v[54:55], v[152:153]
	v_pk_fma_f32 v[150:151], v[232:233], v[124:125], v[150:151]
	v_pk_fma_f32 v[148:149], v[232:233], v[122:123], v[148:149]
	v_pk_fma_f32 v[144:145], v[232:233], v[132:133], v[144:145]
	v_pk_fma_f32 v[140:141], v[232:233], v[126:127], v[140:141]
	v_pk_fma_f32 v[138:139], v[232:233], v[120:121], v[138:139]
	v_pk_fma_f32 v[136:137], v[232:233], v[118:119], v[136:137]
	v_pk_fma_f32 v[134:135], v[232:233], v[116:117], v[134:135]
	v_and_b32_e32 v107, 0xffff0000, v107
	v_pk_fma_f32 v[100:101], v[232:233], v[114:115], v[100:101]
	v_pk_fma_f32 v[78:79], v[232:233], v[112:113], v[78:79]
	v_pk_fma_f32 v[48:49], v[232:233], v[110:111], v[48:49]
	v_pk_fma_f32 v[2:3], v[232:233], v[108:109], v[2:3]
	v_lshlrev_b32_e32 v104, 16, v105
	v_pk_fma_f32 v[166:167], v[234:235], v[56:57], v[166:167]
	v_pk_fma_f32 v[154:155], v[234:235], v[54:55], v[154:155]
	v_pk_fma_f32 v[152:153], v[234:235], v[124:125], v[152:153]
	v_pk_fma_f32 v[150:151], v[234:235], v[122:123], v[150:151]
	v_pk_fma_f32 v[148:149], v[234:235], v[132:133], v[148:149]
	v_pk_fma_f32 v[144:145], v[234:235], v[130:131], v[144:145]
	v_pk_fma_f32 v[140:141], v[234:235], v[120:121], v[140:141]
	v_pk_fma_f32 v[138:139], v[234:235], v[118:119], v[138:139]
	v_pk_fma_f32 v[136:137], v[234:235], v[116:117], v[136:137]
	v_pk_fma_f32 v[134:135], v[234:235], v[114:115], v[134:135]
	v_pk_fma_f32 v[100:101], v[234:235], v[112:113], v[100:101]
	v_and_b32_e32 v105, 0xffff0000, v105
	v_pk_fma_f32 v[78:79], v[234:235], v[110:111], v[78:79]
	v_pk_fma_f32 v[48:49], v[234:235], v[108:109], v[48:49]
	v_pk_fma_f32 v[2:3], v[234:235], v[106:107], v[2:3]
	v_lshlrev_b32_e32 v102, 16, v103
	v_pk_fma_f32 v[166:167], v[236:237], v[54:55], v[166:167]
	v_pk_fma_f32 v[154:155], v[236:237], v[124:125], v[154:155]
	v_pk_fma_f32 v[152:153], v[236:237], v[122:123], v[152:153]
	v_pk_fma_f32 v[150:151], v[236:237], v[132:133], v[150:151]
	v_pk_fma_f32 v[148:149], v[236:237], v[130:131], v[148:149]
	v_pk_fma_f32 v[144:145], v[236:237], v[128:129], v[144:145]
	v_pk_fma_f32 v[140:141], v[236:237], v[118:119], v[140:141]
	v_pk_fma_f32 v[138:139], v[236:237], v[116:117], v[138:139]
	v_pk_fma_f32 v[136:137], v[236:237], v[114:115], v[136:137]
	v_pk_fma_f32 v[134:135], v[236:237], v[112:113], v[134:135]
	v_pk_fma_f32 v[100:101], v[236:237], v[110:111], v[100:101]
	v_pk_fma_f32 v[78:79], v[236:237], v[108:109], v[78:79]
	v_and_b32_e32 v103, 0xffff0000, v103
	v_pk_fma_f32 v[48:49], v[236:237], v[106:107], v[48:49]
	v_pk_fma_f32 v[2:3], v[236:237], v[104:105], v[2:3]
	v_lshlrev_b32_e32 v4, 16, v157
	v_pk_fma_f32 v[166:167], v[238:239], v[124:125], v[166:167]
	v_pk_fma_f32 v[154:155], v[238:239], v[122:123], v[154:155]
	v_pk_fma_f32 v[152:153], v[238:239], v[132:133], v[152:153]
	v_pk_fma_f32 v[150:151], v[238:239], v[130:131], v[150:151]
	v_pk_fma_f32 v[148:149], v[238:239], v[128:129], v[148:149]
	v_pk_fma_f32 v[144:145], v[238:239], v[126:127], v[144:145]
	v_pk_fma_f32 v[140:141], v[238:239], v[116:117], v[140:141]
	v_pk_fma_f32 v[138:139], v[238:239], v[114:115], v[138:139]
	v_pk_fma_f32 v[136:137], v[238:239], v[112:113], v[136:137]
	v_pk_fma_f32 v[134:135], v[238:239], v[110:111], v[134:135]
	v_pk_fma_f32 v[100:101], v[238:239], v[108:109], v[100:101]
	v_pk_fma_f32 v[78:79], v[238:239], v[106:107], v[78:79]
	v_pk_fma_f32 v[48:49], v[238:239], v[104:105], v[48:49]
	v_and_b32_e32 v5, 0xffff0000, v157
	v_pk_fma_f32 v[2:3], v[238:239], v[102:103], v[2:3]
	v_pk_fma_f32 v[166:167], v[240:241], v[122:123], v[166:167]
	v_pk_fma_f32 v[154:155], v[240:241], v[132:133], v[154:155]
	v_pk_fma_f32 v[152:153], v[240:241], v[130:131], v[152:153]
	v_pk_fma_f32 v[150:151], v[240:241], v[128:129], v[150:151]
	v_pk_fma_f32 v[148:149], v[240:241], v[126:127], v[148:149]
	v_pk_fma_f32 v[144:145], v[240:241], v[120:121], v[144:145]
	v_pk_fma_f32 v[140:141], v[240:241], v[114:115], v[140:141]
	v_pk_fma_f32 v[138:139], v[240:241], v[112:113], v[138:139]
	v_pk_fma_f32 v[136:137], v[240:241], v[110:111], v[136:137]
	v_pk_fma_f32 v[134:135], v[240:241], v[108:109], v[134:135]
	v_pk_fma_f32 v[100:101], v[240:241], v[106:107], v[100:101]
	v_pk_fma_f32 v[78:79], v[240:241], v[104:105], v[78:79]
	v_pk_fma_f32 v[48:49], v[240:241], v[102:103], v[48:49]
	v_pk_fma_f32 v[2:3], v[240:241], v[4:5], v[2:3]
	ds_write_b64 v172, v[166:167]
	ds_write_b64 v172, v[154:155] offset:2080
	ds_write_b64 v172, v[152:153] offset:4160
	ds_write_b64 v172, v[150:151] offset:6240
	ds_write_b64 v172, v[148:149] offset:8320
	ds_write_b64 v172, v[144:145] offset:10400
	ds_write_b64 v172, v[140:141] offset:16640
	ds_write_b64 v172, v[138:139] offset:18720
	ds_write_b64 v172, v[136:137] offset:20800
	ds_write_b64 v172, v[134:135] offset:22880
	ds_write_b64 v172, v[100:101] offset:24960
	ds_write_b64 v172, v[78:79] offset:27040
	ds_write_b64 v172, v[48:49] offset:29120
	ds_write_b64 v172, v[2:3] offset:31200
	s_waitcnt vmcnt(0) lgkmcnt(0)
	v_readlane_b32 s37, v253, 17
	v_readlane_b32 s38, v253, 18
	v_readlane_b32 s39, v253, 19
	v_readlane_b32 s42, v253, 22
	v_readlane_b32 s43, v253, 23
	v_readlane_b32 s44, v253, 24
	v_readlane_b32 s45, v253, 25
	v_readlane_b32 s46, v253, 26
	v_readlane_b32 s47, v253, 27
	v_readlane_b32 s48, v253, 28
	v_readlane_b32 s49, v253, 29
	v_readlane_b32 s50, v253, 30
	v_readlane_b32 s51, v253, 31
	s_and_saveexec_b64 s[0:1], s[4:5]
	s_cbranch_execz .LBB0_743
; DI int half_id() { return __builtin_amdgcn_readfirstlane((int)(threadIdx.x >> 8)); }
; DI void hsync_impl(const bool INIT) {
;     ...
;   asm volatile("s_waitcnt vmcnt(0) lgkmcnt(0)" ::: "memory");
;   if ((threadIdx.x & 63) == 0) {
;     const int h2 = 2 * half_id();
;     const unsigned gen = __hip_atomic_load(&hb[h2 + 1], __ATOMIC_RELAXED, __HIP_MEMORY_SCOPE_WORKGROUP);
;     const unsigned old = __hip_atomic_fetch_add(&hb[h2], 1u, __ATOMIC_RELAXED, __HIP_MEMORY_SCOPE_WORKGROUP);
;     if (old == 3u) {
;       __hip_atomic_store(&hb[h2], 0u, __ATOMIC_RELAXED, __HIP_MEMORY_SCOPE_WORKGROUP);
;       asm volatile("s_waitcnt vmcnt(0) lgkmcnt(0)" ::: "memory");
;       __hip_atomic_fetch_add(&hb[h2 + 1], 1u, __ATOMIC_RELAXED, __HIP_MEMORY_SCOPE_WORKGROUP);
;     } else {
;       while (__hip_atomic_load(&hb[h2 + 1], __ATOMIC_RELAXED, __HIP_MEMORY_SCOPE_WORKGROUP) == gen) __builtin_amdgcn_s_sleep(1);
;     }
;   }
;   asm volatile("s_waitcnt vmcnt(0) lgkmcnt(0)" ::: "memory");
; }
	v_readfirstlane_b32 s13, v211
	s_lshr_b32 s13, s13, 5
	s_and_b32 s13, s13, 0x7fffff8
	v_mov_b32_e32 v2, s13
	ds_read_b32 v2, v2 offset:4
	s_mov_b64 s[14:15], exec
	v_mbcnt_lo_u32_b32 v3, s14, 0
	v_mbcnt_hi_u32_b32 v3, s15, v3
	v_cmp_eq_u32_e32 vcc, 0, v3
	s_and_saveexec_b64 s[16:17], vcc
	s_bcnt1_i32_b64 s14, s[14:15]
	v_mov_b32_e32 v4, s13
	v_mov_b32_e32 v5, s14
	ds_add_rtn_u32 v4, v4, v5
	s_or_b64 exec, exec, s[16:17]
	s_waitcnt lgkmcnt(0)
	v_readfirstlane_b32 s14, v4
	s_nop 1
	v_add_u32_e32 v3, s14, v3
	v_cmp_ne_u32_e32 vcc, 3, v3
	s_and_saveexec_b64 s[14:15], vcc
	s_xor_b64 s[14:15], exec, s[14:15]
	s_cbranch_execz .LBB0_740
	v_mov_b32_e32 v3, s13
	ds_read_b32 v3, v3 offset:4
	s_waitcnt lgkmcnt(0)
	v_cmp_ne_u32_e32 vcc, v3, v2
	s_cbranch_vccnz .LBB0_740
